# GEMM mainloops: tile-staging DMAs use SGPR-base + 32-bit VGPR offset form, removing 16 64-bit VALU adds per iteration from the loader waves; on top of mixing edits
# speedup vs baseline: 1.0267x; 1.0267x over previous
.LBB0_41:
	s_add_u32 s40, s36, 0xfffc0080
	s_addc_u32 s41, s37, -1
	s_add_i32 s97, 0, 0x10000
	s_cmp_eq_u32 s90, 12
	s_cselect_b32 s47, s17, s41
	s_cselect_b32 s46, s68, s40
	v_add_u32_e32 v140, s97, v142
	s_cselect_b32 s45, s15, s89
	s_cselect_b32 s44, s69, s88
	s_add_i32 s40, 0, 0x14000
	ds_read_b128 v[146:149], v140
	ds_read_b128 v[150:153], v140 offset:1024
	ds_read_b128 v[154:157], v140 offset:2048
	ds_read_b128 v[158:161], v140 offset:3072
	v_add_u32_e32 v140, s40, v142
	ds_read_b128 v[162:165], v140
	ds_read_b128 v[166:169], v140 offset:1024
	ds_read_b128 v[170:173], v140 offset:2048
	ds_read_b128 v[174:177], v140 offset:3072
	s_add_i32 m0, s51, 0xc000
	ds_read_b128 v[190:193], v145
	ds_read_b128 v[194:197], v145 offset:1024
	ds_read_b128 v[198:201], v145 offset:2048
	ds_read_b128 v[202:205], v145 offset:3072
	ds_read_b128 v[206:209], v145 offset:4096
	ds_read_b128 v[228:231], v145 offset:5120
	ds_read_b128 v[232:235], v145 offset:6144
	ds_read_b128 v[236:239], v145 offset:7168
	global_load_lds_dwordx4 v136, s[36:37]
	s_add_i32 m0, s51, 0xe000
	s_nop 0
	global_load_lds_dwordx4 v138, s[36:37]
	s_waitcnt vmcnt(8)
	s_waitcnt lgkmcnt(0)
	s_barrier
	s_setprio 1
	s_waitcnt lgkmcnt(0)
	v_mfma_f32_16x16x32_bf16 v[124:127], v[146:149], v[190:193], v[124:127]
	v_mfma_f32_16x16x32_bf16 v[116:119], v[154:157], v[190:193], v[116:119]
	v_mfma_f32_16x16x32_bf16 v[108:111], v[146:149], v[198:201], v[108:111]
	v_mfma_f32_16x16x32_bf16 v[100:103], v[154:157], v[198:201], v[100:103]
	v_mfma_f32_16x16x32_bf16 v[92:95], v[146:149], v[206:209], v[92:95]
	v_mfma_f32_16x16x32_bf16 v[84:87], v[154:157], v[206:209], v[84:87]
	v_mfma_f32_16x16x32_bf16 v[76:79], v[146:149], v[232:235], v[76:79]
	v_mfma_f32_16x16x32_bf16 v[68:71], v[154:157], v[232:235], v[68:71]
	v_mfma_f32_16x16x32_bf16 v[124:127], v[150:153], v[194:197], v[124:127]
	v_mfma_f32_16x16x32_bf16 v[116:119], v[158:161], v[194:197], v[116:119]
	v_mfma_f32_16x16x32_bf16 v[108:111], v[150:153], v[202:205], v[108:111]
	v_mfma_f32_16x16x32_bf16 v[100:103], v[158:161], v[202:205], v[100:103]
	v_mfma_f32_16x16x32_bf16 v[92:95], v[150:153], v[228:231], v[92:95]
	v_mfma_f32_16x16x32_bf16 v[84:87], v[158:161], v[228:231], v[84:87]
	v_mfma_f32_16x16x32_bf16 v[76:79], v[150:153], v[236:239], v[76:79]
	v_mfma_f32_16x16x32_bf16 v[68:71], v[158:161], v[236:239], v[68:71]
	s_setprio 0
	s_setprio 1
	v_mfma_f32_16x16x32_bf16 v[128:131], v[162:165], v[190:193], v[128:131]
	v_mfma_f32_16x16x32_bf16 v[120:123], v[170:173], v[190:193], v[120:123]
	v_mfma_f32_16x16x32_bf16 v[112:115], v[162:165], v[198:201], v[112:115]
	v_mfma_f32_16x16x32_bf16 v[104:107], v[170:173], v[198:201], v[104:107]
	v_mfma_f32_16x16x32_bf16 v[96:99], v[162:165], v[206:209], v[96:99]
	v_mfma_f32_16x16x32_bf16 v[88:91], v[170:173], v[206:209], v[88:91]
	v_mfma_f32_16x16x32_bf16 v[80:83], v[162:165], v[232:235], v[80:83]
	v_mfma_f32_16x16x32_bf16 v[72:75], v[170:173], v[232:235], v[72:75]
	v_mfma_f32_16x16x32_bf16 v[128:131], v[166:169], v[194:197], v[128:131]
	v_mfma_f32_16x16x32_bf16 v[120:123], v[174:177], v[194:197], v[120:123]
	v_mfma_f32_16x16x32_bf16 v[112:115], v[166:169], v[202:205], v[112:115]
	v_mfma_f32_16x16x32_bf16 v[104:107], v[174:177], v[202:205], v[104:107]
	v_mfma_f32_16x16x32_bf16 v[96:99], v[166:169], v[228:231], v[96:99]
	v_mfma_f32_16x16x32_bf16 v[88:91], v[174:177], v[228:231], v[88:91]
	v_mfma_f32_16x16x32_bf16 v[80:83], v[166:169], v[236:239], v[80:83]
	v_mfma_f32_16x16x32_bf16 v[72:75], v[174:177], v[236:239], v[72:75]
	s_setprio 0
	s_barrier
	s_add_i32 s41, s97, s50
	s_mov_b32 m0, s41
	ds_read_b128 v[190:193], v145 offset:16384
	ds_read_b128 v[194:197], v145 offset:17408
	ds_read_b128 v[198:201], v145 offset:18432
	ds_read_b128 v[202:205], v145 offset:19456
	ds_read_b128 v[206:209], v145 offset:20480
	ds_read_b128 v[228:231], v145 offset:21504
	ds_read_b128 v[232:235], v145 offset:22528
	ds_read_b128 v[236:239], v145 offset:23552
	global_load_lds_dwordx4 v180, s[44:45]
	s_add_i32 m0, s41, 0x2000
	s_add_u32 vcc_lo, s44, 0x40000
	s_addc_u32 vcc_hi, s45, 0
	s_add_i32 s40, s40, s50
	global_load_lds_dwordx4 v134, s[44:45]
	s_mov_b32 m0, s40
	s_nop 0
	global_load_lds_dwordx4 v180, vcc
	s_add_i32 m0, s40, 0x2000
	s_nop 0
	global_load_lds_dwordx4 v134, vcc
	s_mov_b32 m0, s51
	s_nop 0
	global_load_lds_dwordx4 v0, s[46:47]
	s_mov_b32 m0, s52
	s_nop 0
	global_load_lds_dwordx4 v132, s[46:47]
	s_waitcnt vmcnt(8)
	s_waitcnt lgkmcnt(0)
	s_barrier
	s_setprio 1
	s_waitcnt lgkmcnt(0)
	v_mfma_f32_16x16x32_bf16 v[60:63], v[146:149], v[190:193], v[60:63]
	v_mfma_f32_16x16x32_bf16 v[52:55], v[154:157], v[190:193], v[52:55]
	v_mfma_f32_16x16x32_bf16 v[44:47], v[146:149], v[198:201], v[44:47]
	v_mfma_f32_16x16x32_bf16 v[36:39], v[154:157], v[198:201], v[36:39]
	v_mfma_f32_16x16x32_bf16 v[28:31], v[146:149], v[206:209], v[28:31]
	v_mfma_f32_16x16x32_bf16 v[20:23], v[154:157], v[206:209], v[20:23]
	v_mfma_f32_16x16x32_bf16 v[12:15], v[146:149], v[232:235], v[12:15]
	v_mfma_f32_16x16x32_bf16 v[8:11], v[154:157], v[232:235], v[8:11]
	v_mfma_f32_16x16x32_bf16 v[60:63], v[150:153], v[194:197], v[60:63]
	v_mfma_f32_16x16x32_bf16 v[52:55], v[158:161], v[194:197], v[52:55]
	v_mfma_f32_16x16x32_bf16 v[44:47], v[150:153], v[202:205], v[44:47]
	v_mfma_f32_16x16x32_bf16 v[36:39], v[158:161], v[202:205], v[36:39]
	v_mfma_f32_16x16x32_bf16 v[28:31], v[150:153], v[228:231], v[28:31]
	v_mfma_f32_16x16x32_bf16 v[20:23], v[158:161], v[228:231], v[20:23]
	v_mfma_f32_16x16x32_bf16 v[12:15], v[150:153], v[236:239], v[12:15]
	v_mfma_f32_16x16x32_bf16 v[8:11], v[158:161], v[236:239], v[8:11]
	s_setprio 0
	s_setprio 1
	v_mfma_f32_16x16x32_bf16 v[64:67], v[162:165], v[190:193], v[64:67]
	v_mfma_f32_16x16x32_bf16 v[56:59], v[170:173], v[190:193], v[56:59]
	v_mfma_f32_16x16x32_bf16 v[48:51], v[162:165], v[198:201], v[48:51]
	v_mfma_f32_16x16x32_bf16 v[40:43], v[170:173], v[198:201], v[40:43]
	v_mfma_f32_16x16x32_bf16 v[32:35], v[162:165], v[206:209], v[32:35]
	v_mfma_f32_16x16x32_bf16 v[24:27], v[170:173], v[206:209], v[24:27]
	v_mfma_f32_16x16x32_bf16 v[16:19], v[162:165], v[232:235], v[16:19]
	v_mfma_f32_16x16x32_bf16 v[4:7], v[170:173], v[232:235], v[4:7]
	v_mfma_f32_16x16x32_bf16 v[64:67], v[166:169], v[194:197], v[64:67]
	v_mfma_f32_16x16x32_bf16 v[56:59], v[174:177], v[194:197], v[56:59]
	v_mfma_f32_16x16x32_bf16 v[48:51], v[166:169], v[202:205], v[48:51]
	v_mfma_f32_16x16x32_bf16 v[40:43], v[174:177], v[202:205], v[40:43]
	v_mfma_f32_16x16x32_bf16 v[32:35], v[166:169], v[228:231], v[32:35]
	v_mfma_f32_16x16x32_bf16 v[24:27], v[174:177], v[228:231], v[24:27]
	v_mfma_f32_16x16x32_bf16 v[16:19], v[166:169], v[236:239], v[16:19]
	v_mfma_f32_16x16x32_bf16 v[4:7], v[174:177], v[236:239], v[4:7]
	s_setprio 0
	s_barrier
	s_add_i32 s40, 0, 0x18000
	s_add_i32 s41, 0, 0x1c000
	v_add_u32_e32 v158, s40, v142
	v_add_u32_e32 v174, s41, v142
	ds_read_b128 v[146:149], v158
	ds_read_b128 v[150:153], v158 offset:1024
	ds_read_b128 v[154:157], v158 offset:2048
	ds_read_b128 v[158:161], v158 offset:3072
	ds_read_b128 v[162:165], v174
	ds_read_b128 v[166:169], v174 offset:1024
	ds_read_b128 v[170:173], v174 offset:2048
	ds_read_b128 v[174:177], v174 offset:3072
	s_add_u32 s46, s46, 0x40000
	s_addc_u32 s47, s47, 0
	s_mov_b32 m0, s53
	ds_read_b128 v[190:193], v145 offset:32768
	ds_read_b128 v[194:197], v145 offset:33792
	ds_read_b128 v[198:201], v145 offset:34816
	ds_read_b128 v[202:205], v145 offset:35840
	ds_read_b128 v[206:209], v145 offset:36864
	ds_read_b128 v[228:231], v145 offset:37888
	ds_read_b128 v[232:235], v145 offset:38912
	ds_read_b128 v[236:239], v145 offset:39936
	global_load_lds_dwordx4 v0, s[46:47]
	s_mov_b32 m0, s54
	s_nop 0
	global_load_lds_dwordx4 v132, s[46:47]
	s_waitcnt vmcnt(8)
	s_waitcnt lgkmcnt(0)
	s_barrier
	s_setprio 1
	s_waitcnt lgkmcnt(0)
	v_mfma_f32_16x16x32_bf16 v[124:127], v[146:149], v[190:193], v[124:127]
	v_mfma_f32_16x16x32_bf16 v[116:119], v[154:157], v[190:193], v[116:119]
	v_mfma_f32_16x16x32_bf16 v[108:111], v[146:149], v[198:201], v[108:111]
	v_mfma_f32_16x16x32_bf16 v[100:103], v[154:157], v[198:201], v[100:103]
	v_mfma_f32_16x16x32_bf16 v[92:95], v[146:149], v[206:209], v[92:95]
	v_mfma_f32_16x16x32_bf16 v[84:87], v[154:157], v[206:209], v[84:87]
	v_mfma_f32_16x16x32_bf16 v[76:79], v[146:149], v[232:235], v[76:79]
	v_mfma_f32_16x16x32_bf16 v[68:71], v[154:157], v[232:235], v[68:71]
	v_mfma_f32_16x16x32_bf16 v[124:127], v[150:153], v[194:197], v[124:127]
	v_mfma_f32_16x16x32_bf16 v[116:119], v[158:161], v[194:197], v[116:119]
	v_mfma_f32_16x16x32_bf16 v[108:111], v[150:153], v[202:205], v[108:111]
	v_mfma_f32_16x16x32_bf16 v[100:103], v[158:161], v[202:205], v[100:103]
	v_mfma_f32_16x16x32_bf16 v[92:95], v[150:153], v[228:231], v[92:95]
	v_mfma_f32_16x16x32_bf16 v[84:87], v[158:161], v[228:231], v[84:87]
	v_mfma_f32_16x16x32_bf16 v[76:79], v[150:153], v[236:239], v[76:79]
	v_mfma_f32_16x16x32_bf16 v[68:71], v[158:161], v[236:239], v[68:71]
	s_setprio 0
	s_setprio 1
	v_mfma_f32_16x16x32_bf16 v[128:131], v[162:165], v[190:193], v[128:131]
	v_mfma_f32_16x16x32_bf16 v[120:123], v[170:173], v[190:193], v[120:123]
	v_mfma_f32_16x16x32_bf16 v[112:115], v[162:165], v[198:201], v[112:115]
	v_mfma_f32_16x16x32_bf16 v[104:107], v[170:173], v[198:201], v[104:107]
	v_mfma_f32_16x16x32_bf16 v[96:99], v[162:165], v[206:209], v[96:99]
	v_mfma_f32_16x16x32_bf16 v[88:91], v[170:173], v[206:209], v[88:91]
	v_mfma_f32_16x16x32_bf16 v[80:83], v[162:165], v[232:235], v[80:83]
	v_mfma_f32_16x16x32_bf16 v[72:75], v[170:173], v[232:235], v[72:75]
	v_mfma_f32_16x16x32_bf16 v[128:131], v[166:169], v[194:197], v[128:131]
	v_mfma_f32_16x16x32_bf16 v[120:123], v[174:177], v[194:197], v[120:123]
	v_mfma_f32_16x16x32_bf16 v[112:115], v[166:169], v[202:205], v[112:115]
	v_mfma_f32_16x16x32_bf16 v[104:107], v[174:177], v[202:205], v[104:107]
	v_mfma_f32_16x16x32_bf16 v[96:99], v[166:169], v[228:231], v[96:99]
	v_mfma_f32_16x16x32_bf16 v[88:91], v[174:177], v[228:231], v[88:91]
	v_mfma_f32_16x16x32_bf16 v[80:83], v[166:169], v[236:239], v[80:83]
	v_mfma_f32_16x16x32_bf16 v[72:75], v[174:177], v[236:239], v[72:75]
	s_setprio 0
	s_barrier
	s_add_i32 s40, s40, s50
	s_mov_b32 m0, s40
	ds_read_b128 v[190:193], v145 offset:49152
	ds_read_b128 v[194:197], v145 offset:50176
	ds_read_b128 v[198:201], v145 offset:51200
	ds_read_b128 v[202:205], v145 offset:52224
	ds_read_b128 v[206:209], v145 offset:53248
	ds_read_b128 v[228:231], v145 offset:54272
	ds_read_b128 v[232:235], v145 offset:55296
	ds_read_b128 v[236:239], v145 offset:56320
	s_add_u32 s100, s44, 0x80
	s_addc_u32 s101, s45, 0
	global_load_lds_dwordx4 v180, s[100:101]
	s_add_i32 m0, s40, 0x2000
	s_add_u32 s44, s44, 0x40080
	s_addc_u32 s45, s45, 0
	s_add_i32 s40, s41, s50
	s_add_u32 s100, vcc_lo, 0xfffc0080
	s_addc_u32 s101, vcc_hi, -1
	global_load_lds_dwordx4 v134, s[100:101]
	s_mov_b32 m0, s40
	s_nop 0
	global_load_lds_dwordx4 v180, s[44:45]
	s_add_i32 m0, s40, 0x2000
	s_nop 0
	global_load_lds_dwordx4 v134, s[44:45]
	s_mov_b32 m0, s55
	s_nop 0
	s_add_u32 s100, s46, 0xfffc0080
	s_addc_u32 s101, s47, -1
	global_load_lds_dwordx4 v0, s[100:101]
	s_mov_b32 m0, s58
	s_nop 0
	s_add_u32 s100, s46, 0xfffc0080
	s_addc_u32 s101, s47, -1
	global_load_lds_dwordx4 v132, s[100:101]
	s_waitcnt vmcnt(8)
	s_waitcnt lgkmcnt(0)
	s_barrier
	s_setprio 1
	s_waitcnt lgkmcnt(0)
	v_mfma_f32_16x16x32_bf16 v[60:63], v[146:149], v[190:193], v[60:63]
	v_mfma_f32_16x16x32_bf16 v[52:55], v[154:157], v[190:193], v[52:55]
	v_mfma_f32_16x16x32_bf16 v[44:47], v[146:149], v[198:201], v[44:47]
	v_mfma_f32_16x16x32_bf16 v[36:39], v[154:157], v[198:201], v[36:39]
	v_mfma_f32_16x16x32_bf16 v[28:31], v[146:149], v[206:209], v[28:31]
	v_mfma_f32_16x16x32_bf16 v[20:23], v[154:157], v[206:209], v[20:23]
	v_mfma_f32_16x16x32_bf16 v[12:15], v[146:149], v[232:235], v[12:15]
	v_mfma_f32_16x16x32_bf16 v[8:11], v[154:157], v[232:235], v[8:11]
	v_mfma_f32_16x16x32_bf16 v[60:63], v[150:153], v[194:197], v[60:63]
	v_mfma_f32_16x16x32_bf16 v[52:55], v[158:161], v[194:197], v[52:55]
	v_mfma_f32_16x16x32_bf16 v[44:47], v[150:153], v[202:205], v[44:47]
	v_mfma_f32_16x16x32_bf16 v[36:39], v[158:161], v[202:205], v[36:39]
	v_mfma_f32_16x16x32_bf16 v[28:31], v[150:153], v[228:231], v[28:31]
	v_mfma_f32_16x16x32_bf16 v[20:23], v[158:161], v[228:231], v[20:23]
	v_mfma_f32_16x16x32_bf16 v[12:15], v[150:153], v[236:239], v[12:15]
	v_mfma_f32_16x16x32_bf16 v[8:11], v[158:161], v[236:239], v[8:11]
	s_setprio 0
	s_setprio 1
	v_mfma_f32_16x16x32_bf16 v[64:67], v[162:165], v[190:193], v[64:67]
	v_mfma_f32_16x16x32_bf16 v[56:59], v[170:173], v[190:193], v[56:59]
	v_mfma_f32_16x16x32_bf16 v[48:51], v[162:165], v[198:201], v[48:51]
	v_mfma_f32_16x16x32_bf16 v[40:43], v[170:173], v[198:201], v[40:43]
	v_mfma_f32_16x16x32_bf16 v[32:35], v[162:165], v[206:209], v[32:35]
	v_mfma_f32_16x16x32_bf16 v[24:27], v[170:173], v[206:209], v[24:27]
	v_mfma_f32_16x16x32_bf16 v[16:19], v[162:165], v[232:235], v[16:19]
	v_mfma_f32_16x16x32_bf16 v[4:7], v[170:173], v[232:235], v[4:7]
	v_mfma_f32_16x16x32_bf16 v[64:67], v[166:169], v[194:197], v[64:67]
	v_mfma_f32_16x16x32_bf16 v[56:59], v[174:177], v[194:197], v[56:59]
	v_mfma_f32_16x16x32_bf16 v[48:51], v[166:169], v[202:205], v[48:51]
	v_mfma_f32_16x16x32_bf16 v[40:43], v[174:177], v[202:205], v[40:43]
	v_mfma_f32_16x16x32_bf16 v[32:35], v[166:169], v[228:231], v[32:35]
	v_mfma_f32_16x16x32_bf16 v[24:27], v[174:177], v[228:231], v[24:27]
	v_mfma_f32_16x16x32_bf16 v[16:19], v[166:169], v[236:239], v[16:19]
	v_mfma_f32_16x16x32_bf16 v[4:7], v[174:177], v[236:239], v[4:7]
	s_setprio 0
	s_barrier
	s_add_i32 s90, s90, 2
	s_add_u32 s36, s36, 0x100
	s_addc_u32 s37, s37, 0
	s_add_u32 s88, s88, 0x100
	s_addc_u32 s89, s89, 0
	s_cmp_gt_u32 s90, 13
	s_cbranch_scc0 .LBB0_41
	s_and_b64 vcc, exec, s[10:11]
	s_cbranch_vccz .LBB0_44
	s_barrier

.LBB0_83:
	s_add_u32 s10, s8, 0xfffc0080
	s_addc_u32 s11, s9, -1
	s_add_i32 s40, 0, 0x10000
	s_cmp_eq_u32 vcc_hi, 12
	s_cselect_b32 s53, s27, s11
	s_cselect_b32 s52, s89, s10
	s_cselect_b32 s11, s19, vcc_lo
	s_cselect_b32 s10, s90, s97
	s_add_i32 s25, 0, 0x14000
	v_add_u32_e32 v144, s40, v159
	v_add_u32_e32 v158, s25, v159
	ds_read_b128 v[132:135], v144
	ds_read_b128 v[136:139], v144 offset:1024
	ds_read_b128 v[140:143], v144 offset:2048
	ds_read_b128 v[144:147], v144 offset:3072
	ds_read_b128 v[190:193], v158
	ds_read_b128 v[194:197], v158 offset:1024
	ds_read_b128 v[198:201], v158 offset:2048
	ds_read_b128 v[202:205], v158 offset:3072
	s_add_i32 m0, s49, 0xc000
	ds_read_b128 v[206:209], v179
	ds_read_b128 v[228:231], v179 offset:1024
	ds_read_b128 v[232:235], v179 offset:2048
	ds_read_b128 v[236:239], v179 offset:3072
	ds_read_b128 v[240:243], v179 offset:4096
	ds_read_b128 v[244:247], v179 offset:5120
	ds_read_b128 v[224:227], v179 offset:6144
	ds_read_b128 v[218:221], v179 offset:7168
	global_load_lds_dwordx4 v154, s[8:9]
	s_add_i32 m0, s49, 0xe000
	s_nop 0
	global_load_lds_dwordx4 v156, s[8:9]
	s_waitcnt vmcnt(8)
	s_waitcnt lgkmcnt(0)
	s_barrier
	s_setprio 1
	s_waitcnt lgkmcnt(0)
	v_mfma_f32_16x16x32_bf16 v[128:131], v[132:135], v[206:209], v[128:131]
	v_mfma_f32_16x16x32_bf16 v[124:127], v[140:143], v[206:209], v[124:127]
	v_mfma_f32_16x16x32_bf16 v[112:115], v[132:135], v[232:235], v[112:115]
	v_mfma_f32_16x16x32_bf16 v[108:111], v[140:143], v[232:235], v[108:111]
	v_mfma_f32_16x16x32_bf16 v[96:99], v[132:135], v[240:243], v[96:99]
	v_mfma_f32_16x16x32_bf16 v[92:95], v[140:143], v[240:243], v[92:95]
	v_mfma_f32_16x16x32_bf16 v[80:83], v[132:135], v[224:227], v[80:83]
	v_mfma_f32_16x16x32_bf16 v[76:79], v[140:143], v[224:227], v[76:79]
	v_mfma_f32_16x16x32_bf16 v[128:131], v[136:139], v[228:231], v[128:131]
	v_mfma_f32_16x16x32_bf16 v[124:127], v[144:147], v[228:231], v[124:127]
	v_mfma_f32_16x16x32_bf16 v[112:115], v[136:139], v[236:239], v[112:115]
	v_mfma_f32_16x16x32_bf16 v[108:111], v[144:147], v[236:239], v[108:111]
	v_mfma_f32_16x16x32_bf16 v[96:99], v[136:139], v[244:247], v[96:99]
	v_mfma_f32_16x16x32_bf16 v[92:95], v[144:147], v[244:247], v[92:95]
	v_mfma_f32_16x16x32_bf16 v[80:83], v[136:139], v[218:221], v[80:83]
	v_mfma_f32_16x16x32_bf16 v[76:79], v[144:147], v[218:221], v[76:79]
	s_setprio 0
	s_setprio 1
	v_mfma_f32_16x16x32_bf16 v[120:123], v[190:193], v[206:209], v[120:123]
	v_mfma_f32_16x16x32_bf16 v[116:119], v[198:201], v[206:209], v[116:119]
	v_mfma_f32_16x16x32_bf16 v[104:107], v[190:193], v[232:235], v[104:107]
	v_mfma_f32_16x16x32_bf16 v[100:103], v[198:201], v[232:235], v[100:103]
	v_mfma_f32_16x16x32_bf16 v[88:91], v[190:193], v[240:243], v[88:91]
	v_mfma_f32_16x16x32_bf16 v[84:87], v[198:201], v[240:243], v[84:87]
	v_mfma_f32_16x16x32_bf16 v[72:75], v[190:193], v[224:227], v[72:75]
	v_mfma_f32_16x16x32_bf16 v[68:71], v[198:201], v[224:227], v[68:71]
	v_mfma_f32_16x16x32_bf16 v[120:123], v[194:197], v[228:231], v[120:123]
	v_mfma_f32_16x16x32_bf16 v[116:119], v[202:205], v[228:231], v[116:119]
	v_mfma_f32_16x16x32_bf16 v[104:107], v[194:197], v[236:239], v[104:107]
	v_mfma_f32_16x16x32_bf16 v[100:103], v[202:205], v[236:239], v[100:103]
	v_mfma_f32_16x16x32_bf16 v[88:91], v[194:197], v[244:247], v[88:91]
	v_mfma_f32_16x16x32_bf16 v[84:87], v[202:205], v[244:247], v[84:87]
	v_mfma_f32_16x16x32_bf16 v[72:75], v[194:197], v[218:221], v[72:75]
	v_mfma_f32_16x16x32_bf16 v[68:71], v[202:205], v[218:221], v[68:71]
	s_setprio 0
	s_barrier
	s_add_i32 s40, s40, s55
	s_mov_b32 m0, s40
	ds_read_b128 v[206:209], v179 offset:16384
	ds_read_b128 v[218:221], v179 offset:17408
	ds_read_b128 v[224:227], v179 offset:18432
	ds_read_b128 v[228:231], v179 offset:19456
	ds_read_b128 v[232:235], v179 offset:20480
	ds_read_b128 v[236:239], v179 offset:21504
	ds_read_b128 v[240:243], v179 offset:22528
	ds_read_b128 v[244:247], v179 offset:23552
	global_load_lds_dwordx4 v180, s[10:11]
	s_add_i32 m0, s40, 0x2000
	s_add_u32 s40, s10, 0x40000
	s_addc_u32 s41, s11, 0
	s_add_i32 s25, s25, s55
	global_load_lds_dwordx4 v150, s[10:11]
	s_mov_b32 m0, s25
	s_nop 0
	global_load_lds_dwordx4 v180, s[40:41]
	s_add_i32 m0, s25, 0x2000
	s_nop 0
	global_load_lds_dwordx4 v150, s[40:41]
	s_mov_b32 m0, s49
	s_nop 0
	global_load_lds_dwordx4 v0, s[52:53]
	s_mov_b32 m0, s51
	s_nop 0
	global_load_lds_dwordx4 v148, s[52:53]
	s_waitcnt vmcnt(8)
	s_waitcnt lgkmcnt(0)
	s_barrier
	s_setprio 1
	s_waitcnt lgkmcnt(0)
	v_mfma_f32_16x16x32_bf16 v[64:67], v[132:135], v[206:209], v[64:67]
	v_mfma_f32_16x16x32_bf16 v[60:63], v[140:143], v[206:209], v[60:63]
	v_mfma_f32_16x16x32_bf16 v[48:51], v[132:135], v[224:227], v[48:51]
	v_mfma_f32_16x16x32_bf16 v[44:47], v[140:143], v[224:227], v[44:47]
	v_mfma_f32_16x16x32_bf16 v[32:35], v[132:135], v[232:235], v[32:35]
	v_mfma_f32_16x16x32_bf16 v[28:31], v[140:143], v[232:235], v[28:31]
	v_mfma_f32_16x16x32_bf16 v[16:19], v[132:135], v[240:243], v[16:19]
	v_mfma_f32_16x16x32_bf16 v[12:15], v[140:143], v[240:243], v[12:15]
	v_mfma_f32_16x16x32_bf16 v[64:67], v[136:139], v[218:221], v[64:67]
	v_mfma_f32_16x16x32_bf16 v[60:63], v[144:147], v[218:221], v[60:63]
	v_mfma_f32_16x16x32_bf16 v[48:51], v[136:139], v[228:231], v[48:51]
	v_mfma_f32_16x16x32_bf16 v[44:47], v[144:147], v[228:231], v[44:47]
	v_mfma_f32_16x16x32_bf16 v[32:35], v[136:139], v[236:239], v[32:35]
	v_mfma_f32_16x16x32_bf16 v[28:31], v[144:147], v[236:239], v[28:31]
	v_mfma_f32_16x16x32_bf16 v[16:19], v[136:139], v[244:247], v[16:19]
	v_mfma_f32_16x16x32_bf16 v[12:15], v[144:147], v[244:247], v[12:15]
	s_setprio 0
	s_setprio 1
	v_mfma_f32_16x16x32_bf16 v[56:59], v[190:193], v[206:209], v[56:59]
	v_mfma_f32_16x16x32_bf16 v[52:55], v[198:201], v[206:209], v[52:55]
	v_mfma_f32_16x16x32_bf16 v[40:43], v[190:193], v[224:227], v[40:43]
	v_mfma_f32_16x16x32_bf16 v[36:39], v[198:201], v[224:227], v[36:39]
	v_mfma_f32_16x16x32_bf16 v[24:27], v[190:193], v[232:235], v[24:27]
	v_mfma_f32_16x16x32_bf16 v[20:23], v[198:201], v[232:235], v[20:23]
	v_mfma_f32_16x16x32_bf16 v[8:11], v[190:193], v[240:243], v[8:11]
	v_mfma_f32_16x16x32_bf16 v[4:7], v[198:201], v[240:243], v[4:7]
	v_mfma_f32_16x16x32_bf16 v[56:59], v[194:197], v[218:221], v[56:59]
	v_mfma_f32_16x16x32_bf16 v[52:55], v[202:205], v[218:221], v[52:55]
	v_mfma_f32_16x16x32_bf16 v[40:43], v[194:197], v[228:231], v[40:43]
	v_mfma_f32_16x16x32_bf16 v[36:39], v[202:205], v[228:231], v[36:39]
	v_mfma_f32_16x16x32_bf16 v[24:27], v[194:197], v[236:239], v[24:27]
	v_mfma_f32_16x16x32_bf16 v[20:23], v[202:205], v[236:239], v[20:23]
	v_mfma_f32_16x16x32_bf16 v[8:11], v[194:197], v[244:247], v[8:11]
	v_mfma_f32_16x16x32_bf16 v[4:7], v[202:205], v[244:247], v[4:7]
	s_setprio 0
	s_barrier
	s_add_i32 s25, 0, 0x18000
	s_add_i32 s70, 0, 0x1c000
	v_add_u32_e32 v144, s25, v159
	v_add_u32_e32 v158, s70, v159
	ds_read_b128 v[132:135], v144
	ds_read_b128 v[136:139], v144 offset:1024
	ds_read_b128 v[140:143], v144 offset:2048
	ds_read_b128 v[144:147], v144 offset:3072
	ds_read_b128 v[190:193], v158
	ds_read_b128 v[194:197], v158 offset:1024
	ds_read_b128 v[198:201], v158 offset:2048
	ds_read_b128 v[202:205], v158 offset:3072
	s_add_u32 s40, s52, 0x40000
	s_addc_u32 s41, s53, 0
	s_mov_b32 m0, s58
	ds_read_b128 v[206:209], v179 offset:32768
	ds_read_b128 v[218:221], v179 offset:33792
	ds_read_b128 v[224:227], v179 offset:34816
	ds_read_b128 v[228:231], v179 offset:35840
	ds_read_b128 v[232:235], v179 offset:36864
	ds_read_b128 v[236:239], v179 offset:37888
	ds_read_b128 v[240:243], v179 offset:38912
	ds_read_b128 v[244:247], v179 offset:39936
	global_load_lds_dwordx4 v0, s[40:41]
	s_mov_b32 m0, s59
	s_nop 0
	global_load_lds_dwordx4 v148, s[40:41]
	s_waitcnt vmcnt(8)
	s_waitcnt lgkmcnt(0)
	s_barrier
	s_setprio 1
	s_waitcnt lgkmcnt(0)
	v_mfma_f32_16x16x32_bf16 v[128:131], v[132:135], v[206:209], v[128:131]
	v_mfma_f32_16x16x32_bf16 v[124:127], v[140:143], v[206:209], v[124:127]
	v_mfma_f32_16x16x32_bf16 v[112:115], v[132:135], v[224:227], v[112:115]
	v_mfma_f32_16x16x32_bf16 v[108:111], v[140:143], v[224:227], v[108:111]
	v_mfma_f32_16x16x32_bf16 v[96:99], v[132:135], v[232:235], v[96:99]
	v_mfma_f32_16x16x32_bf16 v[92:95], v[140:143], v[232:235], v[92:95]
	v_mfma_f32_16x16x32_bf16 v[80:83], v[132:135], v[240:243], v[80:83]
	v_mfma_f32_16x16x32_bf16 v[76:79], v[140:143], v[240:243], v[76:79]
	v_mfma_f32_16x16x32_bf16 v[128:131], v[136:139], v[218:221], v[128:131]
	v_mfma_f32_16x16x32_bf16 v[124:127], v[144:147], v[218:221], v[124:127]
	v_mfma_f32_16x16x32_bf16 v[112:115], v[136:139], v[228:231], v[112:115]
	v_mfma_f32_16x16x32_bf16 v[108:111], v[144:147], v[228:231], v[108:111]
	v_mfma_f32_16x16x32_bf16 v[96:99], v[136:139], v[236:239], v[96:99]
	v_mfma_f32_16x16x32_bf16 v[92:95], v[144:147], v[236:239], v[92:95]
	v_mfma_f32_16x16x32_bf16 v[80:83], v[136:139], v[244:247], v[80:83]
	v_mfma_f32_16x16x32_bf16 v[76:79], v[144:147], v[244:247], v[76:79]
	s_setprio 0
	s_setprio 1
	v_mfma_f32_16x16x32_bf16 v[120:123], v[190:193], v[206:209], v[120:123]
	v_mfma_f32_16x16x32_bf16 v[116:119], v[198:201], v[206:209], v[116:119]
	v_mfma_f32_16x16x32_bf16 v[104:107], v[190:193], v[224:227], v[104:107]
	v_mfma_f32_16x16x32_bf16 v[100:103], v[198:201], v[224:227], v[100:103]
	v_mfma_f32_16x16x32_bf16 v[88:91], v[190:193], v[232:235], v[88:91]
	v_mfma_f32_16x16x32_bf16 v[84:87], v[198:201], v[232:235], v[84:87]
	v_mfma_f32_16x16x32_bf16 v[72:75], v[190:193], v[240:243], v[72:75]
	v_mfma_f32_16x16x32_bf16 v[68:71], v[198:201], v[240:243], v[68:71]
	v_mfma_f32_16x16x32_bf16 v[120:123], v[194:197], v[218:221], v[120:123]
	v_mfma_f32_16x16x32_bf16 v[116:119], v[202:205], v[218:221], v[116:119]
	v_mfma_f32_16x16x32_bf16 v[104:107], v[194:197], v[228:231], v[104:107]
	v_mfma_f32_16x16x32_bf16 v[100:103], v[202:205], v[228:231], v[100:103]
	v_mfma_f32_16x16x32_bf16 v[88:91], v[194:197], v[236:239], v[88:91]
	v_mfma_f32_16x16x32_bf16 v[84:87], v[202:205], v[236:239], v[84:87]
	v_mfma_f32_16x16x32_bf16 v[72:75], v[194:197], v[244:247], v[72:75]
	v_mfma_f32_16x16x32_bf16 v[68:71], v[202:205], v[244:247], v[68:71]
	s_setprio 0
	s_barrier
	s_add_i32 s25, s25, s55
	s_mov_b32 m0, s25
	ds_read_b128 v[206:209], v179 offset:49152
	ds_read_b128 v[218:221], v179 offset:50176
	ds_read_b128 v[224:227], v179 offset:51200
	ds_read_b128 v[228:231], v179 offset:52224
	ds_read_b128 v[232:235], v179 offset:53248
	ds_read_b128 v[236:239], v179 offset:54272
	ds_read_b128 v[240:243], v179 offset:55296
	ds_read_b128 v[244:247], v179 offset:56320
	s_add_u32 s100, s10, 0x80
	s_addc_u32 s101, s11, 0
	global_load_lds_dwordx4 v180, s[100:101]
	s_add_i32 m0, s25, 0x2000
	s_add_u32 s10, s10, 0x40080
	s_addc_u32 s11, s11, 0
	s_add_i32 s25, s70, s55
	s_add_u32 s100, s10, 0xfffc0000
	s_addc_u32 s101, s11, -1
	global_load_lds_dwordx4 v150, s[100:101]
	s_mov_b32 m0, s25
	s_nop 0
	global_load_lds_dwordx4 v180, s[10:11]
	s_add_i32 m0, s25, 0x2000
	s_nop 0
	global_load_lds_dwordx4 v150, s[10:11]
	s_mov_b32 m0, s64
	s_nop 0
	s_add_u32 s100, s52, 0x80
	s_addc_u32 s101, s53, 0
	global_load_lds_dwordx4 v0, s[100:101]
	s_mov_b32 m0, s65
	s_nop 0
	s_add_u32 s100, s52, 0x80
	s_addc_u32 s101, s53, 0
	global_load_lds_dwordx4 v148, s[100:101]
	s_waitcnt vmcnt(8)
	s_waitcnt lgkmcnt(0)
	s_barrier
	s_setprio 1
	s_waitcnt lgkmcnt(0)
	v_mfma_f32_16x16x32_bf16 v[64:67], v[132:135], v[206:209], v[64:67]
	v_mfma_f32_16x16x32_bf16 v[60:63], v[140:143], v[206:209], v[60:63]
	v_mfma_f32_16x16x32_bf16 v[48:51], v[132:135], v[224:227], v[48:51]
	v_mfma_f32_16x16x32_bf16 v[44:47], v[140:143], v[224:227], v[44:47]
	v_mfma_f32_16x16x32_bf16 v[32:35], v[132:135], v[232:235], v[32:35]
	v_mfma_f32_16x16x32_bf16 v[28:31], v[140:143], v[232:235], v[28:31]
	v_mfma_f32_16x16x32_bf16 v[16:19], v[132:135], v[240:243], v[16:19]
	v_mfma_f32_16x16x32_bf16 v[12:15], v[140:143], v[240:243], v[12:15]
	v_mfma_f32_16x16x32_bf16 v[64:67], v[136:139], v[218:221], v[64:67]
	v_mfma_f32_16x16x32_bf16 v[60:63], v[144:147], v[218:221], v[60:63]
	v_mfma_f32_16x16x32_bf16 v[48:51], v[136:139], v[228:231], v[48:51]
	v_mfma_f32_16x16x32_bf16 v[44:47], v[144:147], v[228:231], v[44:47]
	v_mfma_f32_16x16x32_bf16 v[32:35], v[136:139], v[236:239], v[32:35]
	v_mfma_f32_16x16x32_bf16 v[28:31], v[144:147], v[236:239], v[28:31]
	v_mfma_f32_16x16x32_bf16 v[16:19], v[136:139], v[244:247], v[16:19]
	v_mfma_f32_16x16x32_bf16 v[12:15], v[144:147], v[244:247], v[12:15]
	s_setprio 0
	s_setprio 1
	v_mfma_f32_16x16x32_bf16 v[56:59], v[190:193], v[206:209], v[56:59]
	v_mfma_f32_16x16x32_bf16 v[52:55], v[198:201], v[206:209], v[52:55]
	v_mfma_f32_16x16x32_bf16 v[40:43], v[190:193], v[224:227], v[40:43]
	v_mfma_f32_16x16x32_bf16 v[36:39], v[198:201], v[224:227], v[36:39]
	v_mfma_f32_16x16x32_bf16 v[24:27], v[190:193], v[232:235], v[24:27]
	v_mfma_f32_16x16x32_bf16 v[20:23], v[198:201], v[232:235], v[20:23]
	v_mfma_f32_16x16x32_bf16 v[8:11], v[190:193], v[240:243], v[8:11]
	v_mfma_f32_16x16x32_bf16 v[4:7], v[198:201], v[240:243], v[4:7]
	v_mfma_f32_16x16x32_bf16 v[56:59], v[194:197], v[218:221], v[56:59]
	v_mfma_f32_16x16x32_bf16 v[52:55], v[202:205], v[218:221], v[52:55]
	v_mfma_f32_16x16x32_bf16 v[40:43], v[194:197], v[228:231], v[40:43]
	v_mfma_f32_16x16x32_bf16 v[36:39], v[202:205], v[228:231], v[36:39]
	v_mfma_f32_16x16x32_bf16 v[24:27], v[194:197], v[236:239], v[24:27]
	v_mfma_f32_16x16x32_bf16 v[20:23], v[202:205], v[236:239], v[20:23]
	v_mfma_f32_16x16x32_bf16 v[8:11], v[194:197], v[244:247], v[8:11]
	v_mfma_f32_16x16x32_bf16 v[4:7], v[202:205], v[244:247], v[4:7]
	s_setprio 0
	s_barrier
	s_add_i32 vcc_hi, vcc_hi, 2
	s_add_u32 s8, s8, 0x100
	s_addc_u32 s9, s9, 0
	s_add_u32 s97, s97, 0x100
	s_addc_u32 vcc_lo, vcc_lo, 0
	s_cmp_gt_u32 vcc_hi, 13
	s_cbranch_scc0 .LBB0_83
	s_and_b64 vcc, exec, s[16:17]
	s_cbranch_vccz .LBB0_86
	s_barrier

.LBB0_142:
	s_add_u32 s25, s36, 0xfffc0080
	s_addc_u32 s40, s37, -1
	s_add_i32 s41, 0, 0x10000
	s_cmp_eq_u32 s88, 12
	s_cselect_b32 s47, s17, s40
	s_cselect_b32 s46, s64, s25
	s_cselect_b32 s45, s15, s69
	s_cselect_b32 s44, s65, s68
	s_add_i32 s25, 0, 0x14000
	v_add_u32_e32 v156, s41, v140
	v_add_u32_e32 v172, s25, v140
	ds_read_b128 v[144:147], v156
	ds_read_b128 v[148:151], v156 offset:1024
	ds_read_b128 v[152:155], v156 offset:2048
	ds_read_b128 v[156:159], v156 offset:3072
	ds_read_b128 v[160:163], v172
	ds_read_b128 v[164:167], v172 offset:1024
	ds_read_b128 v[168:171], v172 offset:2048
	ds_read_b128 v[172:175], v172 offset:3072
	s_add_i32 m0, s49, 0xc000
	ds_read_b128 v[176:179], v143
	ds_read_b128 v[190:193], v143 offset:1024
	ds_read_b128 v[194:197], v143 offset:2048
	ds_read_b128 v[198:201], v143 offset:3072
	ds_read_b128 v[202:205], v143 offset:4096
	ds_read_b128 v[206:209], v143 offset:5120
	ds_read_b128 v[218:221], v143 offset:6144
	ds_read_b128 v[224:227], v143 offset:7168
	global_load_lds_dwordx4 v136, s[36:37]
	s_add_i32 m0, s49, 0xe000
	s_nop 0
	global_load_lds_dwordx4 v138, s[36:37]
	s_waitcnt vmcnt(8)
	s_waitcnt lgkmcnt(0)
	s_barrier
	s_setprio 1
	s_waitcnt lgkmcnt(0)
	v_mfma_f32_16x16x32_bf16 v[128:131], v[144:147], v[176:179], v[128:131]
	v_mfma_f32_16x16x32_bf16 v[124:127], v[152:155], v[176:179], v[124:127]
	v_mfma_f32_16x16x32_bf16 v[120:123], v[144:147], v[194:197], v[120:123]
	v_mfma_f32_16x16x32_bf16 v[112:115], v[152:155], v[194:197], v[112:115]
	v_mfma_f32_16x16x32_bf16 v[96:99], v[144:147], v[202:205], v[96:99]
	v_mfma_f32_16x16x32_bf16 v[92:95], v[152:155], v[202:205], v[92:95]
	v_mfma_f32_16x16x32_bf16 v[88:91], v[144:147], v[218:221], v[88:91]
	v_mfma_f32_16x16x32_bf16 v[80:83], v[152:155], v[218:221], v[80:83]
	v_mfma_f32_16x16x32_bf16 v[128:131], v[148:151], v[190:193], v[128:131]
	v_mfma_f32_16x16x32_bf16 v[124:127], v[156:159], v[190:193], v[124:127]
	v_mfma_f32_16x16x32_bf16 v[120:123], v[148:151], v[198:201], v[120:123]
	v_mfma_f32_16x16x32_bf16 v[112:115], v[156:159], v[198:201], v[112:115]
	v_mfma_f32_16x16x32_bf16 v[96:99], v[148:151], v[206:209], v[96:99]
	v_mfma_f32_16x16x32_bf16 v[92:95], v[156:159], v[206:209], v[92:95]
	v_mfma_f32_16x16x32_bf16 v[88:91], v[148:151], v[224:227], v[88:91]
	v_mfma_f32_16x16x32_bf16 v[80:83], v[156:159], v[224:227], v[80:83]
	s_setprio 0
	s_setprio 1
	v_mfma_f32_16x16x32_bf16 v[116:119], v[160:163], v[176:179], v[116:119]
	v_mfma_f32_16x16x32_bf16 v[108:111], v[168:171], v[176:179], v[108:111]
	v_mfma_f32_16x16x32_bf16 v[104:107], v[160:163], v[194:197], v[104:107]
	v_mfma_f32_16x16x32_bf16 v[100:103], v[168:171], v[194:197], v[100:103]
	v_mfma_f32_16x16x32_bf16 v[84:87], v[160:163], v[202:205], v[84:87]
	v_mfma_f32_16x16x32_bf16 v[76:79], v[168:171], v[202:205], v[76:79]
	v_mfma_f32_16x16x32_bf16 v[72:75], v[160:163], v[218:221], v[72:75]
	v_mfma_f32_16x16x32_bf16 v[68:71], v[168:171], v[218:221], v[68:71]
	v_mfma_f32_16x16x32_bf16 v[116:119], v[164:167], v[190:193], v[116:119]
	v_mfma_f32_16x16x32_bf16 v[108:111], v[172:175], v[190:193], v[108:111]
	v_mfma_f32_16x16x32_bf16 v[104:107], v[164:167], v[198:201], v[104:107]
	v_mfma_f32_16x16x32_bf16 v[100:103], v[172:175], v[198:201], v[100:103]
	v_mfma_f32_16x16x32_bf16 v[84:87], v[164:167], v[206:209], v[84:87]
	v_mfma_f32_16x16x32_bf16 v[76:79], v[172:175], v[206:209], v[76:79]
	v_mfma_f32_16x16x32_bf16 v[72:75], v[164:167], v[224:227], v[72:75]
	v_mfma_f32_16x16x32_bf16 v[68:71], v[172:175], v[224:227], v[68:71]
	s_setprio 0
	s_barrier
	s_add_i32 s40, s41, s48
	s_mov_b32 m0, s40
	ds_read_b128 v[176:179], v143 offset:16384
	ds_read_b128 v[190:193], v143 offset:17408
	ds_read_b128 v[194:197], v143 offset:18432
	ds_read_b128 v[198:201], v143 offset:19456
	ds_read_b128 v[202:205], v143 offset:20480
	ds_read_b128 v[206:209], v143 offset:21504
	ds_read_b128 v[218:221], v143 offset:22528
	ds_read_b128 v[224:227], v143 offset:23552
	global_load_lds_dwordx4 v180, s[44:45]
	s_add_i32 m0, s40, 0x2000
	s_add_u32 s40, s44, 0x40000
	s_addc_u32 s41, s45, 0
	s_add_i32 s25, s25, s48
	global_load_lds_dwordx4 v134, s[44:45]
	s_mov_b32 m0, s25
	s_nop 0
	global_load_lds_dwordx4 v180, s[40:41]
	s_add_i32 m0, s25, 0x2000
	s_nop 0
	global_load_lds_dwordx4 v134, s[40:41]
	s_mov_b32 m0, s49
	s_nop 0
	global_load_lds_dwordx4 v0, s[46:47]
	s_mov_b32 m0, s50
	s_nop 0
	global_load_lds_dwordx4 v132, s[46:47]
	s_waitcnt vmcnt(8)
	s_waitcnt lgkmcnt(0)
	s_barrier
	s_setprio 1
	s_waitcnt lgkmcnt(0)
	v_mfma_f32_16x16x32_bf16 v[64:67], v[144:147], v[176:179], v[64:67]
	v_mfma_f32_16x16x32_bf16 v[60:63], v[152:155], v[176:179], v[60:63]
	v_mfma_f32_16x16x32_bf16 v[56:59], v[144:147], v[194:197], v[56:59]
	v_mfma_f32_16x16x32_bf16 v[48:51], v[152:155], v[194:197], v[48:51]
	v_mfma_f32_16x16x32_bf16 v[32:35], v[144:147], v[202:205], v[32:35]
	v_mfma_f32_16x16x32_bf16 v[28:31], v[152:155], v[202:205], v[28:31]
	v_mfma_f32_16x16x32_bf16 v[24:27], v[144:147], v[218:221], v[24:27]
	v_mfma_f32_16x16x32_bf16 v[16:19], v[152:155], v[218:221], v[16:19]
	v_mfma_f32_16x16x32_bf16 v[64:67], v[148:151], v[190:193], v[64:67]
	v_mfma_f32_16x16x32_bf16 v[60:63], v[156:159], v[190:193], v[60:63]
	v_mfma_f32_16x16x32_bf16 v[56:59], v[148:151], v[198:201], v[56:59]
	v_mfma_f32_16x16x32_bf16 v[48:51], v[156:159], v[198:201], v[48:51]
	v_mfma_f32_16x16x32_bf16 v[32:35], v[148:151], v[206:209], v[32:35]
	v_mfma_f32_16x16x32_bf16 v[28:31], v[156:159], v[206:209], v[28:31]
	v_mfma_f32_16x16x32_bf16 v[24:27], v[148:151], v[224:227], v[24:27]
	v_mfma_f32_16x16x32_bf16 v[16:19], v[156:159], v[224:227], v[16:19]
	s_setprio 0
	s_setprio 1
	v_mfma_f32_16x16x32_bf16 v[52:55], v[160:163], v[176:179], v[52:55]
	v_mfma_f32_16x16x32_bf16 v[44:47], v[168:171], v[176:179], v[44:47]
	v_mfma_f32_16x16x32_bf16 v[40:43], v[160:163], v[194:197], v[40:43]
	v_mfma_f32_16x16x32_bf16 v[36:39], v[168:171], v[194:197], v[36:39]
	v_mfma_f32_16x16x32_bf16 v[20:23], v[160:163], v[202:205], v[20:23]
	v_mfma_f32_16x16x32_bf16 v[12:15], v[168:171], v[202:205], v[12:15]
	v_mfma_f32_16x16x32_bf16 v[8:11], v[160:163], v[218:221], v[8:11]
	v_mfma_f32_16x16x32_bf16 v[4:7], v[168:171], v[218:221], v[4:7]
	v_mfma_f32_16x16x32_bf16 v[52:55], v[164:167], v[190:193], v[52:55]
	v_mfma_f32_16x16x32_bf16 v[44:47], v[172:175], v[190:193], v[44:47]
	v_mfma_f32_16x16x32_bf16 v[40:43], v[164:167], v[198:201], v[40:43]
	v_mfma_f32_16x16x32_bf16 v[36:39], v[172:175], v[198:201], v[36:39]
	v_mfma_f32_16x16x32_bf16 v[20:23], v[164:167], v[206:209], v[20:23]
	v_mfma_f32_16x16x32_bf16 v[12:15], v[172:175], v[206:209], v[12:15]
	v_mfma_f32_16x16x32_bf16 v[8:11], v[164:167], v[224:227], v[8:11]
	v_mfma_f32_16x16x32_bf16 v[4:7], v[172:175], v[224:227], v[4:7]
	s_setprio 0
	s_barrier
	s_add_i32 s25, 0, 0x18000
	s_add_i32 s70, 0, 0x1c000
	v_add_u32_e32 v156, s25, v140
	v_add_u32_e32 v172, s70, v140
	ds_read_b128 v[144:147], v156
	ds_read_b128 v[148:151], v156 offset:1024
	ds_read_b128 v[152:155], v156 offset:2048
	ds_read_b128 v[156:159], v156 offset:3072
	ds_read_b128 v[160:163], v172
	ds_read_b128 v[164:167], v172 offset:1024
	ds_read_b128 v[168:171], v172 offset:2048
	ds_read_b128 v[172:175], v172 offset:3072
	s_add_u32 s40, s46, 0x40000
	s_addc_u32 s41, s47, 0
	s_mov_b32 m0, s51
	ds_read_b128 v[176:179], v143 offset:32768
	ds_read_b128 v[190:193], v143 offset:33792
	ds_read_b128 v[194:197], v143 offset:34816
	ds_read_b128 v[198:201], v143 offset:35840
	ds_read_b128 v[202:205], v143 offset:36864
	ds_read_b128 v[206:209], v143 offset:37888
	ds_read_b128 v[218:221], v143 offset:38912
	ds_read_b128 v[224:227], v143 offset:39936
	global_load_lds_dwordx4 v0, s[40:41]
	s_mov_b32 m0, s52
	s_nop 0
	global_load_lds_dwordx4 v132, s[40:41]
	s_waitcnt vmcnt(8)
	s_waitcnt lgkmcnt(0)
	s_barrier
	s_setprio 1
	s_waitcnt lgkmcnt(0)
	v_mfma_f32_16x16x32_bf16 v[128:131], v[144:147], v[176:179], v[128:131]
	v_mfma_f32_16x16x32_bf16 v[124:127], v[152:155], v[176:179], v[124:127]
	v_mfma_f32_16x16x32_bf16 v[120:123], v[144:147], v[194:197], v[120:123]
	v_mfma_f32_16x16x32_bf16 v[112:115], v[152:155], v[194:197], v[112:115]
	v_mfma_f32_16x16x32_bf16 v[96:99], v[144:147], v[202:205], v[96:99]
	v_mfma_f32_16x16x32_bf16 v[92:95], v[152:155], v[202:205], v[92:95]
	v_mfma_f32_16x16x32_bf16 v[88:91], v[144:147], v[218:221], v[88:91]
	v_mfma_f32_16x16x32_bf16 v[80:83], v[152:155], v[218:221], v[80:83]
	v_mfma_f32_16x16x32_bf16 v[128:131], v[148:151], v[190:193], v[128:131]
	v_mfma_f32_16x16x32_bf16 v[124:127], v[156:159], v[190:193], v[124:127]
	v_mfma_f32_16x16x32_bf16 v[120:123], v[148:151], v[198:201], v[120:123]
	v_mfma_f32_16x16x32_bf16 v[112:115], v[156:159], v[198:201], v[112:115]
	v_mfma_f32_16x16x32_bf16 v[96:99], v[148:151], v[206:209], v[96:99]
	v_mfma_f32_16x16x32_bf16 v[92:95], v[156:159], v[206:209], v[92:95]
	v_mfma_f32_16x16x32_bf16 v[88:91], v[148:151], v[224:227], v[88:91]
	v_mfma_f32_16x16x32_bf16 v[80:83], v[156:159], v[224:227], v[80:83]
	s_setprio 0
	s_setprio 1
	v_mfma_f32_16x16x32_bf16 v[116:119], v[160:163], v[176:179], v[116:119]
	v_mfma_f32_16x16x32_bf16 v[108:111], v[168:171], v[176:179], v[108:111]
	v_mfma_f32_16x16x32_bf16 v[104:107], v[160:163], v[194:197], v[104:107]
	v_mfma_f32_16x16x32_bf16 v[100:103], v[168:171], v[194:197], v[100:103]
	v_mfma_f32_16x16x32_bf16 v[84:87], v[160:163], v[202:205], v[84:87]
	v_mfma_f32_16x16x32_bf16 v[76:79], v[168:171], v[202:205], v[76:79]
	v_mfma_f32_16x16x32_bf16 v[72:75], v[160:163], v[218:221], v[72:75]
	v_mfma_f32_16x16x32_bf16 v[68:71], v[168:171], v[218:221], v[68:71]
	v_mfma_f32_16x16x32_bf16 v[116:119], v[164:167], v[190:193], v[116:119]
	v_mfma_f32_16x16x32_bf16 v[108:111], v[172:175], v[190:193], v[108:111]
	v_mfma_f32_16x16x32_bf16 v[104:107], v[164:167], v[198:201], v[104:107]
	v_mfma_f32_16x16x32_bf16 v[100:103], v[172:175], v[198:201], v[100:103]
	v_mfma_f32_16x16x32_bf16 v[84:87], v[164:167], v[206:209], v[84:87]
	v_mfma_f32_16x16x32_bf16 v[76:79], v[172:175], v[206:209], v[76:79]
	v_mfma_f32_16x16x32_bf16 v[72:75], v[164:167], v[224:227], v[72:75]
	v_mfma_f32_16x16x32_bf16 v[68:71], v[172:175], v[224:227], v[68:71]
	s_setprio 0
	s_barrier
	s_add_i32 s25, s25, s48
	s_mov_b32 m0, s25
	ds_read_b128 v[176:179], v143 offset:49152
	ds_read_b128 v[190:193], v143 offset:50176
	ds_read_b128 v[194:197], v143 offset:51200
	ds_read_b128 v[198:201], v143 offset:52224
	ds_read_b128 v[202:205], v143 offset:53248
	ds_read_b128 v[206:209], v143 offset:54272
	ds_read_b128 v[218:221], v143 offset:55296
	ds_read_b128 v[224:227], v143 offset:56320
	s_add_u32 s100, s44, 0x80
	s_addc_u32 s101, s45, 0
	global_load_lds_dwordx4 v180, s[100:101]
	s_add_i32 m0, s25, 0x2000
	s_add_u32 s40, s44, 0x40080
	s_addc_u32 s41, s45, 0
	s_add_i32 s25, s70, s48
	s_add_u32 s100, s44, 0x80
	s_addc_u32 s101, s45, 0
	global_load_lds_dwordx4 v134, s[100:101]
	s_mov_b32 m0, s25
	s_nop 0
	global_load_lds_dwordx4 v180, s[40:41]
	s_add_i32 m0, s25, 0x2000
	s_nop 0
	global_load_lds_dwordx4 v134, s[40:41]
	s_mov_b32 m0, s53
	s_nop 0
	s_add_u32 s100, s46, 0x80
	s_addc_u32 s101, s47, 0
	global_load_lds_dwordx4 v0, s[100:101]
	s_mov_b32 m0, s54
	s_nop 0
	s_add_u32 s100, s46, 0x80
	s_addc_u32 s101, s47, 0
	global_load_lds_dwordx4 v132, s[100:101]
	s_waitcnt vmcnt(8)
	s_waitcnt lgkmcnt(0)
	s_barrier
	s_setprio 1
	s_waitcnt lgkmcnt(0)
	v_mfma_f32_16x16x32_bf16 v[64:67], v[144:147], v[176:179], v[64:67]
	v_mfma_f32_16x16x32_bf16 v[60:63], v[152:155], v[176:179], v[60:63]
	v_mfma_f32_16x16x32_bf16 v[56:59], v[144:147], v[194:197], v[56:59]
	v_mfma_f32_16x16x32_bf16 v[48:51], v[152:155], v[194:197], v[48:51]
	v_mfma_f32_16x16x32_bf16 v[32:35], v[144:147], v[202:205], v[32:35]
	v_mfma_f32_16x16x32_bf16 v[28:31], v[152:155], v[202:205], v[28:31]
	v_mfma_f32_16x16x32_bf16 v[24:27], v[144:147], v[218:221], v[24:27]
	v_mfma_f32_16x16x32_bf16 v[16:19], v[152:155], v[218:221], v[16:19]
	v_mfma_f32_16x16x32_bf16 v[64:67], v[148:151], v[190:193], v[64:67]
	v_mfma_f32_16x16x32_bf16 v[60:63], v[156:159], v[190:193], v[60:63]
	v_mfma_f32_16x16x32_bf16 v[56:59], v[148:151], v[198:201], v[56:59]
	v_mfma_f32_16x16x32_bf16 v[48:51], v[156:159], v[198:201], v[48:51]
	v_mfma_f32_16x16x32_bf16 v[32:35], v[148:151], v[206:209], v[32:35]
	v_mfma_f32_16x16x32_bf16 v[28:31], v[156:159], v[206:209], v[28:31]
	v_mfma_f32_16x16x32_bf16 v[24:27], v[148:151], v[224:227], v[24:27]
	v_mfma_f32_16x16x32_bf16 v[16:19], v[156:159], v[224:227], v[16:19]
	s_setprio 0
	s_setprio 1
	v_mfma_f32_16x16x32_bf16 v[52:55], v[160:163], v[176:179], v[52:55]
	v_mfma_f32_16x16x32_bf16 v[44:47], v[168:171], v[176:179], v[44:47]
	v_mfma_f32_16x16x32_bf16 v[40:43], v[160:163], v[194:197], v[40:43]
	v_mfma_f32_16x16x32_bf16 v[36:39], v[168:171], v[194:197], v[36:39]
	v_mfma_f32_16x16x32_bf16 v[20:23], v[160:163], v[202:205], v[20:23]
	v_mfma_f32_16x16x32_bf16 v[12:15], v[168:171], v[202:205], v[12:15]
	v_mfma_f32_16x16x32_bf16 v[8:11], v[160:163], v[218:221], v[8:11]
	v_mfma_f32_16x16x32_bf16 v[4:7], v[168:171], v[218:221], v[4:7]
	v_mfma_f32_16x16x32_bf16 v[52:55], v[164:167], v[190:193], v[52:55]
	v_mfma_f32_16x16x32_bf16 v[44:47], v[172:175], v[190:193], v[44:47]
	v_mfma_f32_16x16x32_bf16 v[40:43], v[164:167], v[198:201], v[40:43]
	v_mfma_f32_16x16x32_bf16 v[36:39], v[172:175], v[198:201], v[36:39]
	v_mfma_f32_16x16x32_bf16 v[20:23], v[164:167], v[206:209], v[20:23]
	v_mfma_f32_16x16x32_bf16 v[12:15], v[172:175], v[206:209], v[12:15]
	v_mfma_f32_16x16x32_bf16 v[8:11], v[164:167], v[224:227], v[8:11]
	v_mfma_f32_16x16x32_bf16 v[4:7], v[172:175], v[224:227], v[4:7]
	s_setprio 0
	s_barrier
	s_add_i32 s88, s88, 2
	s_add_u32 s36, s36, 0x100
	s_addc_u32 s37, s37, 0
	s_add_u32 s68, s68, 0x100
	s_addc_u32 s69, s69, 0
	s_cmp_gt_u32 s88, 13
	s_cbranch_scc0 .LBB0_142
	s_and_b64 vcc, exec, s[12:13]
	s_cbranch_vccz .LBB0_145
	s_barrier

.LBB0_181:
	s_add_u32 s25, s10, 0xfffc0080
	s_addc_u32 s40, s11, -1
	s_add_i32 s41, 0, 0x10000
	s_cmp_eq_u32 s68, 12
	s_cselect_b32 s49, s37, s40
	s_cselect_b32 s48, s36, s25
	s_cselect_b32 s47, s19, s65
	s_cselect_b32 s46, s27, s64
	s_add_i32 s25, 0, 0x14000
	v_add_u32_e32 v144, s41, v187
	v_add_u32_e32 v170, s25, v187
	ds_read_b128 v[132:135], v144
	ds_read_b128 v[136:139], v144 offset:1024
	ds_read_b128 v[140:143], v144 offset:2048
	ds_read_b128 v[144:147], v144 offset:3072
	ds_read_b128 v[148:151], v170
	ds_read_b128 v[152:155], v170 offset:1024
	ds_read_b128 v[156:159], v170 offset:2048
	ds_read_b128 v[170:173], v170 offset:3072
	s_add_i32 m0, s51, 0xc000
	ds_read_b128 v[174:177], v194
	ds_read_b128 v[196:199], v194 offset:1024
	ds_read_b128 v[200:203], v194 offset:2048
	ds_read_b128 v[204:207], v194 offset:3072
	ds_read_b128 v[208:211], v194 offset:4096
	ds_read_b128 v[218:221], v194 offset:5120
	ds_read_b128 v[224:227], v194 offset:6144
	ds_read_b128 v[228:231], v194 offset:7168
	global_load_lds_dwordx4 v166, s[10:11]
	s_add_i32 m0, s51, 0xe000
	s_nop 0
	global_load_lds_dwordx4 v168, s[10:11]
	s_waitcnt vmcnt(8)
	s_waitcnt lgkmcnt(0)
	s_barrier
	s_setprio 1
	s_waitcnt lgkmcnt(0)
	v_mfma_f32_16x16x32_bf16 v[128:131], v[132:135], v[174:177], v[128:131]
	v_mfma_f32_16x16x32_bf16 v[124:127], v[140:143], v[174:177], v[124:127]
	v_mfma_f32_16x16x32_bf16 v[112:115], v[132:135], v[200:203], v[112:115]
	v_mfma_f32_16x16x32_bf16 v[108:111], v[140:143], v[200:203], v[108:111]
	v_mfma_f32_16x16x32_bf16 v[96:99], v[132:135], v[208:211], v[96:99]
	v_mfma_f32_16x16x32_bf16 v[92:95], v[140:143], v[208:211], v[92:95]
	v_mfma_f32_16x16x32_bf16 v[80:83], v[132:135], v[224:227], v[80:83]
	v_mfma_f32_16x16x32_bf16 v[76:79], v[140:143], v[224:227], v[76:79]
	v_mfma_f32_16x16x32_bf16 v[128:131], v[136:139], v[196:199], v[128:131]
	v_mfma_f32_16x16x32_bf16 v[124:127], v[144:147], v[196:199], v[124:127]
	v_mfma_f32_16x16x32_bf16 v[112:115], v[136:139], v[204:207], v[112:115]
	v_mfma_f32_16x16x32_bf16 v[108:111], v[144:147], v[204:207], v[108:111]
	v_mfma_f32_16x16x32_bf16 v[96:99], v[136:139], v[218:221], v[96:99]
	v_mfma_f32_16x16x32_bf16 v[92:95], v[144:147], v[218:221], v[92:95]
	v_mfma_f32_16x16x32_bf16 v[80:83], v[136:139], v[228:231], v[80:83]
	v_mfma_f32_16x16x32_bf16 v[76:79], v[144:147], v[228:231], v[76:79]
	s_setprio 0
	s_setprio 1
	v_mfma_f32_16x16x32_bf16 v[120:123], v[148:151], v[174:177], v[120:123]
	v_mfma_f32_16x16x32_bf16 v[116:119], v[156:159], v[174:177], v[116:119]
	v_mfma_f32_16x16x32_bf16 v[104:107], v[148:151], v[200:203], v[104:107]
	v_mfma_f32_16x16x32_bf16 v[100:103], v[156:159], v[200:203], v[100:103]
	v_mfma_f32_16x16x32_bf16 v[88:91], v[148:151], v[208:211], v[88:91]
	v_mfma_f32_16x16x32_bf16 v[84:87], v[156:159], v[208:211], v[84:87]
	v_mfma_f32_16x16x32_bf16 v[72:75], v[148:151], v[224:227], v[72:75]
	v_mfma_f32_16x16x32_bf16 v[68:71], v[156:159], v[224:227], v[68:71]
	v_mfma_f32_16x16x32_bf16 v[120:123], v[152:155], v[196:199], v[120:123]
	v_mfma_f32_16x16x32_bf16 v[116:119], v[170:173], v[196:199], v[116:119]
	v_mfma_f32_16x16x32_bf16 v[104:107], v[152:155], v[204:207], v[104:107]
	v_mfma_f32_16x16x32_bf16 v[100:103], v[170:173], v[204:207], v[100:103]
	v_mfma_f32_16x16x32_bf16 v[88:91], v[152:155], v[218:221], v[88:91]
	v_mfma_f32_16x16x32_bf16 v[84:87], v[170:173], v[218:221], v[84:87]
	v_mfma_f32_16x16x32_bf16 v[72:75], v[152:155], v[228:231], v[72:75]
	v_mfma_f32_16x16x32_bf16 v[68:71], v[170:173], v[228:231], v[68:71]
	s_setprio 0
	s_barrier
	s_add_i32 s40, s41, s50
	s_mov_b32 m0, s40
	ds_read_b128 v[174:177], v194 offset:16384
	ds_read_b128 v[196:199], v194 offset:17408
	ds_read_b128 v[200:203], v194 offset:18432
	ds_read_b128 v[204:207], v194 offset:19456
	ds_read_b128 v[208:211], v194 offset:20480
	ds_read_b128 v[218:221], v194 offset:21504
	ds_read_b128 v[224:227], v194 offset:22528
	ds_read_b128 v[228:231], v194 offset:23552
	global_load_lds_dwordx4 v162, s[46:47]
	s_add_i32 m0, s40, 0x2000
	s_add_u32 s40, s46, 0x40000
	s_addc_u32 s41, s47, 0
	s_add_i32 s25, s25, s50
	global_load_lds_dwordx4 v0, s[46:47]
	s_mov_b32 m0, s25
	s_nop 0
	global_load_lds_dwordx4 v162, s[40:41]
	s_add_i32 m0, s25, 0x2000
	s_nop 0
	global_load_lds_dwordx4 v0, s[40:41]
	s_mov_b32 m0, s51
	s_nop 0
	global_load_lds_dwordx4 v164, s[48:49]
	s_mov_b32 m0, s52
	s_nop 0
	global_load_lds_dwordx4 v160, s[48:49]
	s_waitcnt vmcnt(8)
	s_waitcnt lgkmcnt(0)
	s_barrier
	s_setprio 1
	s_waitcnt lgkmcnt(0)
	v_mfma_f32_16x16x32_bf16 v[64:67], v[132:135], v[174:177], v[64:67]
	v_mfma_f32_16x16x32_bf16 v[60:63], v[140:143], v[174:177], v[60:63]
	v_mfma_f32_16x16x32_bf16 v[48:51], v[132:135], v[200:203], v[48:51]
	v_mfma_f32_16x16x32_bf16 v[44:47], v[140:143], v[200:203], v[44:47]
	v_mfma_f32_16x16x32_bf16 v[32:35], v[132:135], v[208:211], v[32:35]
	v_mfma_f32_16x16x32_bf16 v[28:31], v[140:143], v[208:211], v[28:31]
	v_mfma_f32_16x16x32_bf16 v[16:19], v[132:135], v[224:227], v[16:19]
	v_mfma_f32_16x16x32_bf16 v[12:15], v[140:143], v[224:227], v[12:15]
	v_mfma_f32_16x16x32_bf16 v[64:67], v[136:139], v[196:199], v[64:67]
	v_mfma_f32_16x16x32_bf16 v[60:63], v[144:147], v[196:199], v[60:63]
	v_mfma_f32_16x16x32_bf16 v[48:51], v[136:139], v[204:207], v[48:51]
	v_mfma_f32_16x16x32_bf16 v[44:47], v[144:147], v[204:207], v[44:47]
	v_mfma_f32_16x16x32_bf16 v[32:35], v[136:139], v[218:221], v[32:35]
	v_mfma_f32_16x16x32_bf16 v[28:31], v[144:147], v[218:221], v[28:31]
	v_mfma_f32_16x16x32_bf16 v[16:19], v[136:139], v[228:231], v[16:19]
	v_mfma_f32_16x16x32_bf16 v[12:15], v[144:147], v[228:231], v[12:15]
	s_setprio 0
	s_setprio 1
	v_mfma_f32_16x16x32_bf16 v[56:59], v[148:151], v[174:177], v[56:59]
	v_mfma_f32_16x16x32_bf16 v[52:55], v[156:159], v[174:177], v[52:55]
	v_mfma_f32_16x16x32_bf16 v[40:43], v[148:151], v[200:203], v[40:43]
	v_mfma_f32_16x16x32_bf16 v[36:39], v[156:159], v[200:203], v[36:39]
	v_mfma_f32_16x16x32_bf16 v[24:27], v[148:151], v[208:211], v[24:27]
	v_mfma_f32_16x16x32_bf16 v[20:23], v[156:159], v[208:211], v[20:23]
	v_mfma_f32_16x16x32_bf16 v[8:11], v[148:151], v[224:227], v[8:11]
	v_mfma_f32_16x16x32_bf16 v[4:7], v[156:159], v[224:227], v[4:7]
	v_mfma_f32_16x16x32_bf16 v[56:59], v[152:155], v[196:199], v[56:59]
	v_mfma_f32_16x16x32_bf16 v[52:55], v[170:173], v[196:199], v[52:55]
	v_mfma_f32_16x16x32_bf16 v[40:43], v[152:155], v[204:207], v[40:43]
	v_mfma_f32_16x16x32_bf16 v[36:39], v[170:173], v[204:207], v[36:39]
	v_mfma_f32_16x16x32_bf16 v[24:27], v[152:155], v[218:221], v[24:27]
	v_mfma_f32_16x16x32_bf16 v[20:23], v[170:173], v[218:221], v[20:23]
	v_mfma_f32_16x16x32_bf16 v[8:11], v[152:155], v[228:231], v[8:11]
	v_mfma_f32_16x16x32_bf16 v[4:7], v[170:173], v[228:231], v[4:7]
	s_setprio 0
	s_barrier
	s_add_i32 s25, 0, 0x18000
	s_add_i32 s69, 0, 0x1c000
	v_add_u32_e32 v144, s25, v187
	v_add_u32_e32 v170, s69, v187
	ds_read_b128 v[132:135], v144
	ds_read_b128 v[136:139], v144 offset:1024
	ds_read_b128 v[140:143], v144 offset:2048
	ds_read_b128 v[144:147], v144 offset:3072
	ds_read_b128 v[148:151], v170
	ds_read_b128 v[152:155], v170 offset:1024
	ds_read_b128 v[156:159], v170 offset:2048
	ds_read_b128 v[170:173], v170 offset:3072
	s_add_u32 s40, s48, 0x40000
	s_addc_u32 s41, s49, 0
	s_mov_b32 m0, s53
	ds_read_b128 v[174:177], v194 offset:32768
	ds_read_b128 v[196:199], v194 offset:33792
	ds_read_b128 v[200:203], v194 offset:34816
	ds_read_b128 v[204:207], v194 offset:35840
	ds_read_b128 v[208:211], v194 offset:36864
	ds_read_b128 v[218:221], v194 offset:37888
	ds_read_b128 v[224:227], v194 offset:38912
	ds_read_b128 v[228:231], v194 offset:39936
	global_load_lds_dwordx4 v164, s[40:41]
	s_mov_b32 m0, s54
	s_nop 0
	global_load_lds_dwordx4 v160, s[40:41]
	s_waitcnt vmcnt(8)
	s_waitcnt lgkmcnt(0)
	s_barrier
	s_setprio 1
	s_waitcnt lgkmcnt(0)
	v_mfma_f32_16x16x32_bf16 v[128:131], v[132:135], v[174:177], v[128:131]
	v_mfma_f32_16x16x32_bf16 v[124:127], v[140:143], v[174:177], v[124:127]
	v_mfma_f32_16x16x32_bf16 v[112:115], v[132:135], v[200:203], v[112:115]
	v_mfma_f32_16x16x32_bf16 v[108:111], v[140:143], v[200:203], v[108:111]
	v_mfma_f32_16x16x32_bf16 v[96:99], v[132:135], v[208:211], v[96:99]
	v_mfma_f32_16x16x32_bf16 v[92:95], v[140:143], v[208:211], v[92:95]
	v_mfma_f32_16x16x32_bf16 v[80:83], v[132:135], v[224:227], v[80:83]
	v_mfma_f32_16x16x32_bf16 v[76:79], v[140:143], v[224:227], v[76:79]
	v_mfma_f32_16x16x32_bf16 v[128:131], v[136:139], v[196:199], v[128:131]
	v_mfma_f32_16x16x32_bf16 v[124:127], v[144:147], v[196:199], v[124:127]
	v_mfma_f32_16x16x32_bf16 v[112:115], v[136:139], v[204:207], v[112:115]
	v_mfma_f32_16x16x32_bf16 v[108:111], v[144:147], v[204:207], v[108:111]
	v_mfma_f32_16x16x32_bf16 v[96:99], v[136:139], v[218:221], v[96:99]
	v_mfma_f32_16x16x32_bf16 v[92:95], v[144:147], v[218:221], v[92:95]
	v_mfma_f32_16x16x32_bf16 v[80:83], v[136:139], v[228:231], v[80:83]
	v_mfma_f32_16x16x32_bf16 v[76:79], v[144:147], v[228:231], v[76:79]
	s_setprio 0
	s_setprio 1
	v_mfma_f32_16x16x32_bf16 v[120:123], v[148:151], v[174:177], v[120:123]
	v_mfma_f32_16x16x32_bf16 v[116:119], v[156:159], v[174:177], v[116:119]
	v_mfma_f32_16x16x32_bf16 v[104:107], v[148:151], v[200:203], v[104:107]
	v_mfma_f32_16x16x32_bf16 v[100:103], v[156:159], v[200:203], v[100:103]
	v_mfma_f32_16x16x32_bf16 v[88:91], v[148:151], v[208:211], v[88:91]
	v_mfma_f32_16x16x32_bf16 v[84:87], v[156:159], v[208:211], v[84:87]
	v_mfma_f32_16x16x32_bf16 v[72:75], v[148:151], v[224:227], v[72:75]
	v_mfma_f32_16x16x32_bf16 v[68:71], v[156:159], v[224:227], v[68:71]
	v_mfma_f32_16x16x32_bf16 v[120:123], v[152:155], v[196:199], v[120:123]
	v_mfma_f32_16x16x32_bf16 v[116:119], v[170:173], v[196:199], v[116:119]
	v_mfma_f32_16x16x32_bf16 v[104:107], v[152:155], v[204:207], v[104:107]
	v_mfma_f32_16x16x32_bf16 v[100:103], v[170:173], v[204:207], v[100:103]
	v_mfma_f32_16x16x32_bf16 v[88:91], v[152:155], v[218:221], v[88:91]
	v_mfma_f32_16x16x32_bf16 v[84:87], v[170:173], v[218:221], v[84:87]
	v_mfma_f32_16x16x32_bf16 v[72:75], v[152:155], v[228:231], v[72:75]
	v_mfma_f32_16x16x32_bf16 v[68:71], v[170:173], v[228:231], v[68:71]
	s_setprio 0
	s_barrier
	s_add_i32 s25, s25, s50
	s_mov_b32 m0, s25
	ds_read_b128 v[174:177], v194 offset:49152
	ds_read_b128 v[196:199], v194 offset:50176
	ds_read_b128 v[200:203], v194 offset:51200
	ds_read_b128 v[204:207], v194 offset:52224
	ds_read_b128 v[208:211], v194 offset:53248
	ds_read_b128 v[218:221], v194 offset:54272
	ds_read_b128 v[224:227], v194 offset:55296
	ds_read_b128 v[228:231], v194 offset:56320
	s_add_u32 s100, s46, 0x80
	s_addc_u32 s101, s47, 0
	global_load_lds_dwordx4 v162, s[100:101]
	s_add_i32 m0, s25, 0x2000
	s_add_u32 s40, s46, 0x40080
	s_addc_u32 s41, s47, 0
	s_add_i32 s25, s69, s50
	s_add_u32 s100, s46, 0x80
	s_addc_u32 s101, s47, 0
	global_load_lds_dwordx4 v0, s[100:101]
	s_mov_b32 m0, s25
	s_nop 0
	global_load_lds_dwordx4 v162, s[40:41]
	s_add_i32 m0, s25, 0x2000
	s_nop 0
	global_load_lds_dwordx4 v0, s[40:41]
	s_mov_b32 m0, s55
	s_nop 0
	s_add_u32 s100, s48, 0x80
	s_addc_u32 s101, s49, 0
	global_load_lds_dwordx4 v164, s[100:101]
	s_mov_b32 m0, s58
	s_nop 0
	s_add_u32 s100, s48, 0x80
	s_addc_u32 s101, s49, 0
	global_load_lds_dwordx4 v160, s[100:101]
	s_waitcnt vmcnt(8)
	s_waitcnt lgkmcnt(0)
	s_barrier
	s_setprio 1
	s_waitcnt lgkmcnt(0)
	v_mfma_f32_16x16x32_bf16 v[64:67], v[132:135], v[174:177], v[64:67]
	v_mfma_f32_16x16x32_bf16 v[60:63], v[140:143], v[174:177], v[60:63]
	v_mfma_f32_16x16x32_bf16 v[48:51], v[132:135], v[200:203], v[48:51]
	v_mfma_f32_16x16x32_bf16 v[44:47], v[140:143], v[200:203], v[44:47]
	v_mfma_f32_16x16x32_bf16 v[32:35], v[132:135], v[208:211], v[32:35]
	v_mfma_f32_16x16x32_bf16 v[28:31], v[140:143], v[208:211], v[28:31]
	v_mfma_f32_16x16x32_bf16 v[16:19], v[132:135], v[224:227], v[16:19]
	v_mfma_f32_16x16x32_bf16 v[12:15], v[140:143], v[224:227], v[12:15]
	v_mfma_f32_16x16x32_bf16 v[64:67], v[136:139], v[196:199], v[64:67]
	v_mfma_f32_16x16x32_bf16 v[60:63], v[144:147], v[196:199], v[60:63]
	v_mfma_f32_16x16x32_bf16 v[48:51], v[136:139], v[204:207], v[48:51]
	v_mfma_f32_16x16x32_bf16 v[44:47], v[144:147], v[204:207], v[44:47]
	v_mfma_f32_16x16x32_bf16 v[32:35], v[136:139], v[218:221], v[32:35]
	v_mfma_f32_16x16x32_bf16 v[28:31], v[144:147], v[218:221], v[28:31]
	v_mfma_f32_16x16x32_bf16 v[16:19], v[136:139], v[228:231], v[16:19]
	v_mfma_f32_16x16x32_bf16 v[12:15], v[144:147], v[228:231], v[12:15]
	s_setprio 0
	s_setprio 1
	v_mfma_f32_16x16x32_bf16 v[56:59], v[148:151], v[174:177], v[56:59]
	v_mfma_f32_16x16x32_bf16 v[52:55], v[156:159], v[174:177], v[52:55]
	v_mfma_f32_16x16x32_bf16 v[40:43], v[148:151], v[200:203], v[40:43]
	v_mfma_f32_16x16x32_bf16 v[36:39], v[156:159], v[200:203], v[36:39]
	v_mfma_f32_16x16x32_bf16 v[24:27], v[148:151], v[208:211], v[24:27]
	v_mfma_f32_16x16x32_bf16 v[20:23], v[156:159], v[208:211], v[20:23]
	v_mfma_f32_16x16x32_bf16 v[8:11], v[148:151], v[224:227], v[8:11]
	v_mfma_f32_16x16x32_bf16 v[4:7], v[156:159], v[224:227], v[4:7]
	v_mfma_f32_16x16x32_bf16 v[56:59], v[152:155], v[196:199], v[56:59]
	v_mfma_f32_16x16x32_bf16 v[52:55], v[170:173], v[196:199], v[52:55]
	v_mfma_f32_16x16x32_bf16 v[40:43], v[152:155], v[204:207], v[40:43]
	v_mfma_f32_16x16x32_bf16 v[36:39], v[170:173], v[204:207], v[36:39]
	v_mfma_f32_16x16x32_bf16 v[24:27], v[152:155], v[218:221], v[24:27]
	v_mfma_f32_16x16x32_bf16 v[20:23], v[170:173], v[218:221], v[20:23]
	v_mfma_f32_16x16x32_bf16 v[8:11], v[152:155], v[228:231], v[8:11]
	v_mfma_f32_16x16x32_bf16 v[4:7], v[170:173], v[228:231], v[4:7]
	s_setprio 0
	s_barrier
	s_add_i32 s68, s68, 2
	s_add_u32 s10, s10, 0x100
	s_addc_u32 s11, s11, 0
	s_add_u32 s64, s64, 0x100
	s_addc_u32 s65, s65, 0
	s_cmp_gt_u32 s68, 13
	s_cbranch_scc0 .LBB0_181
	s_and_b64 vcc, exec, s[14:15]
	s_cbranch_vccz .LBB0_184
	s_barrier

.LBB0_231:
	s_add_u32 s12, s10, 0xfffc0080
	s_addc_u32 s13, s11, -1
	s_add_i32 s25, 0, 0x10000
	s_cmp_eq_u32 s97, 12
	s_cselect_b32 s47, s27, s13
	s_cselect_b32 s46, s69, s12
	s_cselect_b32 s13, s19, s90
	s_cselect_b32 s12, s88, s89
	s_add_i32 s50, 0, 0x14000
	v_add_u32_e32 v144, s25, v159
	v_add_u32_e32 v158, s50, v159
	ds_read_b128 v[132:135], v144
	ds_read_b128 v[136:139], v144 offset:1024
	ds_read_b128 v[140:143], v144 offset:2048
	ds_read_b128 v[144:147], v144 offset:3072
	ds_read_b128 v[190:193], v158
	ds_read_b128 v[194:197], v158 offset:1024
	ds_read_b128 v[198:201], v158 offset:2048
	ds_read_b128 v[202:205], v158 offset:3072
	s_add_i32 m0, s49, 0xc000
	ds_read_b128 v[206:209], v179
	ds_read_b128 v[218:221], v179 offset:1024
	ds_read_b128 v[224:227], v179 offset:2048
	ds_read_b128 v[228:231], v179 offset:3072
	ds_read_b128 v[232:235], v179 offset:4096
	ds_read_b128 v[236:239], v179 offset:5120
	ds_read_b128 v[240:243], v179 offset:6144
	ds_read_b128 v[244:247], v179 offset:7168
	global_load_lds_dwordx4 v154, s[10:11]
	s_add_i32 m0, s49, 0xe000
	s_nop 0
	global_load_lds_dwordx4 v156, s[10:11]
	s_waitcnt vmcnt(8)
	s_waitcnt lgkmcnt(0)
	s_barrier
	s_setprio 1
	s_waitcnt lgkmcnt(0)
	v_mfma_f32_16x16x32_bf16 v[128:131], v[132:135], v[206:209], v[128:131]
	v_mfma_f32_16x16x32_bf16 v[124:127], v[140:143], v[206:209], v[124:127]
	v_mfma_f32_16x16x32_bf16 v[112:115], v[132:135], v[224:227], v[112:115]
	v_mfma_f32_16x16x32_bf16 v[108:111], v[140:143], v[224:227], v[108:111]
	v_mfma_f32_16x16x32_bf16 v[96:99], v[132:135], v[232:235], v[96:99]
	v_mfma_f32_16x16x32_bf16 v[92:95], v[140:143], v[232:235], v[92:95]
	v_mfma_f32_16x16x32_bf16 v[80:83], v[132:135], v[240:243], v[80:83]
	v_mfma_f32_16x16x32_bf16 v[76:79], v[140:143], v[240:243], v[76:79]
	v_mfma_f32_16x16x32_bf16 v[128:131], v[136:139], v[218:221], v[128:131]
	v_mfma_f32_16x16x32_bf16 v[124:127], v[144:147], v[218:221], v[124:127]
	v_mfma_f32_16x16x32_bf16 v[112:115], v[136:139], v[228:231], v[112:115]
	v_mfma_f32_16x16x32_bf16 v[108:111], v[144:147], v[228:231], v[108:111]
	v_mfma_f32_16x16x32_bf16 v[96:99], v[136:139], v[236:239], v[96:99]
	v_mfma_f32_16x16x32_bf16 v[92:95], v[144:147], v[236:239], v[92:95]
	v_mfma_f32_16x16x32_bf16 v[80:83], v[136:139], v[244:247], v[80:83]
	v_mfma_f32_16x16x32_bf16 v[76:79], v[144:147], v[244:247], v[76:79]
	s_setprio 0
	s_setprio 1
	v_mfma_f32_16x16x32_bf16 v[120:123], v[190:193], v[206:209], v[120:123]
	v_mfma_f32_16x16x32_bf16 v[116:119], v[198:201], v[206:209], v[116:119]
	v_mfma_f32_16x16x32_bf16 v[104:107], v[190:193], v[224:227], v[104:107]
	v_mfma_f32_16x16x32_bf16 v[100:103], v[198:201], v[224:227], v[100:103]
	v_mfma_f32_16x16x32_bf16 v[88:91], v[190:193], v[232:235], v[88:91]
	v_mfma_f32_16x16x32_bf16 v[84:87], v[198:201], v[232:235], v[84:87]
	v_mfma_f32_16x16x32_bf16 v[72:75], v[190:193], v[240:243], v[72:75]
	v_mfma_f32_16x16x32_bf16 v[68:71], v[198:201], v[240:243], v[68:71]
	v_mfma_f32_16x16x32_bf16 v[120:123], v[194:197], v[218:221], v[120:123]
	v_mfma_f32_16x16x32_bf16 v[116:119], v[202:205], v[218:221], v[116:119]
	v_mfma_f32_16x16x32_bf16 v[104:107], v[194:197], v[228:231], v[104:107]
	v_mfma_f32_16x16x32_bf16 v[100:103], v[202:205], v[228:231], v[100:103]
	v_mfma_f32_16x16x32_bf16 v[88:91], v[194:197], v[236:239], v[88:91]
	v_mfma_f32_16x16x32_bf16 v[84:87], v[202:205], v[236:239], v[84:87]
	v_mfma_f32_16x16x32_bf16 v[72:75], v[194:197], v[244:247], v[72:75]
	v_mfma_f32_16x16x32_bf16 v[68:71], v[202:205], v[244:247], v[68:71]
	s_setprio 0
	s_barrier
	s_add_i32 s25, s25, s48
	s_mov_b32 m0, s25
	ds_read_b128 v[206:209], v179 offset:16384
	ds_read_b128 v[218:221], v179 offset:17408
	ds_read_b128 v[224:227], v179 offset:18432
	ds_read_b128 v[228:231], v179 offset:19456
	ds_read_b128 v[232:235], v179 offset:20480
	ds_read_b128 v[236:239], v179 offset:21504
	ds_read_b128 v[240:243], v179 offset:22528
	ds_read_b128 v[244:247], v179 offset:23552
	global_load_lds_dwordx4 v180, s[12:13]
	s_add_i32 m0, s25, 0x2000
	s_add_u32 s40, s12, 0x40000
	s_addc_u32 s41, s13, 0
	s_add_i32 s25, s50, s48
	global_load_lds_dwordx4 v150, s[12:13]
	s_mov_b32 m0, s25
	s_nop 0
	global_load_lds_dwordx4 v180, s[40:41]
	s_add_i32 m0, s25, 0x2000
	s_nop 0
	global_load_lds_dwordx4 v150, s[40:41]
	s_mov_b32 m0, s49
	s_nop 0
	global_load_lds_dwordx4 v0, s[46:47]
	s_mov_b32 m0, s52
	s_nop 0
	global_load_lds_dwordx4 v148, s[46:47]
	s_waitcnt vmcnt(8)
	s_waitcnt lgkmcnt(0)
	s_barrier
	s_setprio 1
	s_waitcnt lgkmcnt(0)
	v_mfma_f32_16x16x32_bf16 v[64:67], v[132:135], v[206:209], v[64:67]
	v_mfma_f32_16x16x32_bf16 v[60:63], v[140:143], v[206:209], v[60:63]
	v_mfma_f32_16x16x32_bf16 v[48:51], v[132:135], v[224:227], v[48:51]
	v_mfma_f32_16x16x32_bf16 v[44:47], v[140:143], v[224:227], v[44:47]
	v_mfma_f32_16x16x32_bf16 v[32:35], v[132:135], v[232:235], v[32:35]
	v_mfma_f32_16x16x32_bf16 v[28:31], v[140:143], v[232:235], v[28:31]
	v_mfma_f32_16x16x32_bf16 v[16:19], v[132:135], v[240:243], v[16:19]
	v_mfma_f32_16x16x32_bf16 v[12:15], v[140:143], v[240:243], v[12:15]
	v_mfma_f32_16x16x32_bf16 v[64:67], v[136:139], v[218:221], v[64:67]
	v_mfma_f32_16x16x32_bf16 v[60:63], v[144:147], v[218:221], v[60:63]
	v_mfma_f32_16x16x32_bf16 v[48:51], v[136:139], v[228:231], v[48:51]
	v_mfma_f32_16x16x32_bf16 v[44:47], v[144:147], v[228:231], v[44:47]
	v_mfma_f32_16x16x32_bf16 v[32:35], v[136:139], v[236:239], v[32:35]
	v_mfma_f32_16x16x32_bf16 v[28:31], v[144:147], v[236:239], v[28:31]
	v_mfma_f32_16x16x32_bf16 v[16:19], v[136:139], v[244:247], v[16:19]
	v_mfma_f32_16x16x32_bf16 v[12:15], v[144:147], v[244:247], v[12:15]
	s_setprio 0
	s_setprio 1
	v_mfma_f32_16x16x32_bf16 v[56:59], v[190:193], v[206:209], v[56:59]
	v_mfma_f32_16x16x32_bf16 v[52:55], v[198:201], v[206:209], v[52:55]
	v_mfma_f32_16x16x32_bf16 v[40:43], v[190:193], v[224:227], v[40:43]
	v_mfma_f32_16x16x32_bf16 v[36:39], v[198:201], v[224:227], v[36:39]
	v_mfma_f32_16x16x32_bf16 v[24:27], v[190:193], v[232:235], v[24:27]
	v_mfma_f32_16x16x32_bf16 v[20:23], v[198:201], v[232:235], v[20:23]
	v_mfma_f32_16x16x32_bf16 v[8:11], v[190:193], v[240:243], v[8:11]
	v_mfma_f32_16x16x32_bf16 v[4:7], v[198:201], v[240:243], v[4:7]
	v_mfma_f32_16x16x32_bf16 v[56:59], v[194:197], v[218:221], v[56:59]
	v_mfma_f32_16x16x32_bf16 v[52:55], v[202:205], v[218:221], v[52:55]
	v_mfma_f32_16x16x32_bf16 v[40:43], v[194:197], v[228:231], v[40:43]
	v_mfma_f32_16x16x32_bf16 v[36:39], v[202:205], v[228:231], v[36:39]
	v_mfma_f32_16x16x32_bf16 v[24:27], v[194:197], v[236:239], v[24:27]
	v_mfma_f32_16x16x32_bf16 v[20:23], v[202:205], v[236:239], v[20:23]
	v_mfma_f32_16x16x32_bf16 v[8:11], v[194:197], v[244:247], v[8:11]
	v_mfma_f32_16x16x32_bf16 v[4:7], v[202:205], v[244:247], v[4:7]
	s_setprio 0
	s_barrier
	s_add_i32 s25, 0, 0x18000
	s_add_i32 s50, 0, 0x1c000
	v_add_u32_e32 v144, s25, v159
	v_add_u32_e32 v158, s50, v159
	ds_read_b128 v[132:135], v144
	ds_read_b128 v[136:139], v144 offset:1024
	ds_read_b128 v[140:143], v144 offset:2048
	ds_read_b128 v[144:147], v144 offset:3072
	ds_read_b128 v[190:193], v158
	ds_read_b128 v[194:197], v158 offset:1024
	ds_read_b128 v[198:201], v158 offset:2048
	ds_read_b128 v[202:205], v158 offset:3072
	s_add_u32 s40, s46, 0x40000
	s_addc_u32 s41, s47, 0
	s_mov_b32 m0, s53
	ds_read_b128 v[206:209], v179 offset:32768
	ds_read_b128 v[218:221], v179 offset:33792
	ds_read_b128 v[224:227], v179 offset:34816
	ds_read_b128 v[228:231], v179 offset:35840
	ds_read_b128 v[232:235], v179 offset:36864
	ds_read_b128 v[236:239], v179 offset:37888
	ds_read_b128 v[240:243], v179 offset:38912
	ds_read_b128 v[244:247], v179 offset:39936
	global_load_lds_dwordx4 v0, s[40:41]
	s_mov_b32 m0, s54
	s_nop 0
	global_load_lds_dwordx4 v148, s[40:41]
	s_waitcnt vmcnt(8)
	s_waitcnt lgkmcnt(0)
	s_barrier
	s_setprio 1
	s_waitcnt lgkmcnt(0)
	v_mfma_f32_16x16x32_bf16 v[128:131], v[132:135], v[206:209], v[128:131]
	v_mfma_f32_16x16x32_bf16 v[124:127], v[140:143], v[206:209], v[124:127]
	v_mfma_f32_16x16x32_bf16 v[112:115], v[132:135], v[224:227], v[112:115]
	v_mfma_f32_16x16x32_bf16 v[108:111], v[140:143], v[224:227], v[108:111]
	v_mfma_f32_16x16x32_bf16 v[96:99], v[132:135], v[232:235], v[96:99]
	v_mfma_f32_16x16x32_bf16 v[92:95], v[140:143], v[232:235], v[92:95]
	v_mfma_f32_16x16x32_bf16 v[80:83], v[132:135], v[240:243], v[80:83]
	v_mfma_f32_16x16x32_bf16 v[76:79], v[140:143], v[240:243], v[76:79]
	v_mfma_f32_16x16x32_bf16 v[128:131], v[136:139], v[218:221], v[128:131]
	v_mfma_f32_16x16x32_bf16 v[124:127], v[144:147], v[218:221], v[124:127]
	v_mfma_f32_16x16x32_bf16 v[112:115], v[136:139], v[228:231], v[112:115]
	v_mfma_f32_16x16x32_bf16 v[108:111], v[144:147], v[228:231], v[108:111]
	v_mfma_f32_16x16x32_bf16 v[96:99], v[136:139], v[236:239], v[96:99]
	v_mfma_f32_16x16x32_bf16 v[92:95], v[144:147], v[236:239], v[92:95]
	v_mfma_f32_16x16x32_bf16 v[80:83], v[136:139], v[244:247], v[80:83]
	v_mfma_f32_16x16x32_bf16 v[76:79], v[144:147], v[244:247], v[76:79]
	s_setprio 0
	s_setprio 1
	v_mfma_f32_16x16x32_bf16 v[120:123], v[190:193], v[206:209], v[120:123]
	v_mfma_f32_16x16x32_bf16 v[116:119], v[198:201], v[206:209], v[116:119]
	v_mfma_f32_16x16x32_bf16 v[104:107], v[190:193], v[224:227], v[104:107]
	v_mfma_f32_16x16x32_bf16 v[100:103], v[198:201], v[224:227], v[100:103]
	v_mfma_f32_16x16x32_bf16 v[88:91], v[190:193], v[232:235], v[88:91]
	v_mfma_f32_16x16x32_bf16 v[84:87], v[198:201], v[232:235], v[84:87]
	v_mfma_f32_16x16x32_bf16 v[72:75], v[190:193], v[240:243], v[72:75]
	v_mfma_f32_16x16x32_bf16 v[68:71], v[198:201], v[240:243], v[68:71]
	v_mfma_f32_16x16x32_bf16 v[120:123], v[194:197], v[218:221], v[120:123]
	v_mfma_f32_16x16x32_bf16 v[116:119], v[202:205], v[218:221], v[116:119]
	v_mfma_f32_16x16x32_bf16 v[104:107], v[194:197], v[228:231], v[104:107]
	v_mfma_f32_16x16x32_bf16 v[100:103], v[202:205], v[228:231], v[100:103]
	v_mfma_f32_16x16x32_bf16 v[88:91], v[194:197], v[236:239], v[88:91]
	v_mfma_f32_16x16x32_bf16 v[84:87], v[202:205], v[236:239], v[84:87]
	v_mfma_f32_16x16x32_bf16 v[72:75], v[194:197], v[244:247], v[72:75]
	v_mfma_f32_16x16x32_bf16 v[68:71], v[202:205], v[244:247], v[68:71]
	s_setprio 0
	s_barrier
	s_add_i32 s25, s25, s48
	s_mov_b32 m0, s25
	ds_read_b128 v[206:209], v179 offset:49152
	ds_read_b128 v[218:221], v179 offset:50176
	ds_read_b128 v[224:227], v179 offset:51200
	ds_read_b128 v[228:231], v179 offset:52224
	ds_read_b128 v[232:235], v179 offset:53248
	ds_read_b128 v[236:239], v179 offset:54272
	ds_read_b128 v[240:243], v179 offset:55296
	ds_read_b128 v[244:247], v179 offset:56320
	s_add_u32 s100, s12, 0x80
	s_addc_u32 s101, s13, 0
	global_load_lds_dwordx4 v180, s[100:101]
	s_add_i32 m0, s25, 0x2000
	s_add_u32 s12, s12, 0x40080
	s_addc_u32 s13, s13, 0
	s_add_i32 s25, s50, s48
	s_add_u32 s100, s12, 0xfffc0000
	s_addc_u32 s101, s13, -1
	global_load_lds_dwordx4 v150, s[100:101]
	s_mov_b32 m0, s25
	s_nop 0
	global_load_lds_dwordx4 v180, s[12:13]
	s_add_i32 m0, s25, 0x2000
	s_nop 0
	global_load_lds_dwordx4 v150, s[12:13]
	s_mov_b32 m0, s55
	s_nop 0
	s_add_u32 s100, s46, 0x80
	s_addc_u32 s101, s47, 0
	global_load_lds_dwordx4 v0, s[100:101]
	s_mov_b32 m0, s58
	s_nop 0
	s_add_u32 s100, s46, 0x80
	s_addc_u32 s101, s47, 0
	global_load_lds_dwordx4 v148, s[100:101]
	s_waitcnt vmcnt(8)
	s_waitcnt lgkmcnt(0)
	s_barrier
	s_setprio 1
	s_waitcnt lgkmcnt(0)
	v_mfma_f32_16x16x32_bf16 v[64:67], v[132:135], v[206:209], v[64:67]
	v_mfma_f32_16x16x32_bf16 v[60:63], v[140:143], v[206:209], v[60:63]
	v_mfma_f32_16x16x32_bf16 v[48:51], v[132:135], v[224:227], v[48:51]
	v_mfma_f32_16x16x32_bf16 v[44:47], v[140:143], v[224:227], v[44:47]
	v_mfma_f32_16x16x32_bf16 v[32:35], v[132:135], v[232:235], v[32:35]
	v_mfma_f32_16x16x32_bf16 v[28:31], v[140:143], v[232:235], v[28:31]
	v_mfma_f32_16x16x32_bf16 v[16:19], v[132:135], v[240:243], v[16:19]
	v_mfma_f32_16x16x32_bf16 v[12:15], v[140:143], v[240:243], v[12:15]
	v_mfma_f32_16x16x32_bf16 v[64:67], v[136:139], v[218:221], v[64:67]
	v_mfma_f32_16x16x32_bf16 v[60:63], v[144:147], v[218:221], v[60:63]
	v_mfma_f32_16x16x32_bf16 v[48:51], v[136:139], v[228:231], v[48:51]
	v_mfma_f32_16x16x32_bf16 v[44:47], v[144:147], v[228:231], v[44:47]
	v_mfma_f32_16x16x32_bf16 v[32:35], v[136:139], v[236:239], v[32:35]
	v_mfma_f32_16x16x32_bf16 v[28:31], v[144:147], v[236:239], v[28:31]
	v_mfma_f32_16x16x32_bf16 v[16:19], v[136:139], v[244:247], v[16:19]
	v_mfma_f32_16x16x32_bf16 v[12:15], v[144:147], v[244:247], v[12:15]
	s_setprio 0
	s_setprio 1
	v_mfma_f32_16x16x32_bf16 v[56:59], v[190:193], v[206:209], v[56:59]
	v_mfma_f32_16x16x32_bf16 v[52:55], v[198:201], v[206:209], v[52:55]
	v_mfma_f32_16x16x32_bf16 v[40:43], v[190:193], v[224:227], v[40:43]
	v_mfma_f32_16x16x32_bf16 v[36:39], v[198:201], v[224:227], v[36:39]
	v_mfma_f32_16x16x32_bf16 v[24:27], v[190:193], v[232:235], v[24:27]
	v_mfma_f32_16x16x32_bf16 v[20:23], v[198:201], v[232:235], v[20:23]
	v_mfma_f32_16x16x32_bf16 v[8:11], v[190:193], v[240:243], v[8:11]
	v_mfma_f32_16x16x32_bf16 v[4:7], v[198:201], v[240:243], v[4:7]
	v_mfma_f32_16x16x32_bf16 v[56:59], v[194:197], v[218:221], v[56:59]
	v_mfma_f32_16x16x32_bf16 v[52:55], v[202:205], v[218:221], v[52:55]
	v_mfma_f32_16x16x32_bf16 v[40:43], v[194:197], v[228:231], v[40:43]
	v_mfma_f32_16x16x32_bf16 v[36:39], v[202:205], v[228:231], v[36:39]
	v_mfma_f32_16x16x32_bf16 v[24:27], v[194:197], v[236:239], v[24:27]
	v_mfma_f32_16x16x32_bf16 v[20:23], v[202:205], v[236:239], v[20:23]
	v_mfma_f32_16x16x32_bf16 v[8:11], v[194:197], v[244:247], v[8:11]
	v_mfma_f32_16x16x32_bf16 v[4:7], v[202:205], v[244:247], v[4:7]
	s_setprio 0
	s_barrier
	s_add_i32 s97, s97, 2
	s_add_u32 s10, s10, 0x100
	s_addc_u32 s11, s11, 0
	s_add_u32 s89, s89, 0x100
	s_addc_u32 s90, s90, 0
	s_cmp_gt_u32 s97, 13
	s_cbranch_scc0 .LBB0_231
	s_and_b64 vcc, exec, s[16:17]
	s_cbranch_vccz .LBB0_234
	s_barrier

.LBB0_334:
	s_add_u32 s25, s44, 0xfffc0080
	s_addc_u32 s40, s45, -1
	s_add_i32 s41, 0, 0x10000
	s_cmp_eq_u32 s88, 12
	s_cselect_b32 s49, s19, s40
	s_cselect_b32 s48, s64, s25
	s_cselect_b32 s47, s17, s69
	s_cselect_b32 s46, s65, s68
	s_add_i32 s25, 0, 0x14000
	v_add_u32_e32 v144, s41, v187
	v_add_u32_e32 v170, s25, v187
	ds_read_b128 v[132:135], v144
	ds_read_b128 v[136:139], v144 offset:1024
	ds_read_b128 v[140:143], v144 offset:2048
	ds_read_b128 v[144:147], v144 offset:3072
	ds_read_b128 v[148:151], v170
	ds_read_b128 v[152:155], v170 offset:1024
	ds_read_b128 v[156:159], v170 offset:2048
	ds_read_b128 v[170:173], v170 offset:3072
	s_add_i32 m0, s51, 0xc000
	ds_read_b128 v[174:177], v194
	ds_read_b128 v[196:199], v194 offset:1024
	ds_read_b128 v[200:203], v194 offset:2048
	ds_read_b128 v[204:207], v194 offset:3072
	ds_read_b128 v[208:211], v194 offset:4096
	ds_read_b128 v[218:221], v194 offset:5120
	ds_read_b128 v[224:227], v194 offset:6144
	ds_read_b128 v[228:231], v194 offset:7168
	global_load_lds_dwordx4 v166, s[44:45]
	s_add_i32 m0, s51, 0xe000
	s_nop 0
	global_load_lds_dwordx4 v168, s[44:45]
	s_waitcnt vmcnt(8)
	s_waitcnt lgkmcnt(0)
	s_barrier
	s_setprio 1
	s_waitcnt lgkmcnt(0)
	v_mfma_f32_16x16x32_bf16 v[128:131], v[132:135], v[174:177], v[128:131]
	v_mfma_f32_16x16x32_bf16 v[124:127], v[140:143], v[174:177], v[124:127]
	v_mfma_f32_16x16x32_bf16 v[112:115], v[132:135], v[200:203], v[112:115]
	v_mfma_f32_16x16x32_bf16 v[108:111], v[140:143], v[200:203], v[108:111]
	v_mfma_f32_16x16x32_bf16 v[96:99], v[132:135], v[208:211], v[96:99]
	v_mfma_f32_16x16x32_bf16 v[92:95], v[140:143], v[208:211], v[92:95]
	v_mfma_f32_16x16x32_bf16 v[80:83], v[132:135], v[224:227], v[80:83]
	v_mfma_f32_16x16x32_bf16 v[76:79], v[140:143], v[224:227], v[76:79]
	v_mfma_f32_16x16x32_bf16 v[128:131], v[136:139], v[196:199], v[128:131]
	v_mfma_f32_16x16x32_bf16 v[124:127], v[144:147], v[196:199], v[124:127]
	v_mfma_f32_16x16x32_bf16 v[112:115], v[136:139], v[204:207], v[112:115]
	v_mfma_f32_16x16x32_bf16 v[108:111], v[144:147], v[204:207], v[108:111]
	v_mfma_f32_16x16x32_bf16 v[96:99], v[136:139], v[218:221], v[96:99]
	v_mfma_f32_16x16x32_bf16 v[92:95], v[144:147], v[218:221], v[92:95]
	v_mfma_f32_16x16x32_bf16 v[80:83], v[136:139], v[228:231], v[80:83]
	v_mfma_f32_16x16x32_bf16 v[76:79], v[144:147], v[228:231], v[76:79]
	s_setprio 0
	s_setprio 1
	v_mfma_f32_16x16x32_bf16 v[120:123], v[148:151], v[174:177], v[120:123]
	v_mfma_f32_16x16x32_bf16 v[116:119], v[156:159], v[174:177], v[116:119]
	v_mfma_f32_16x16x32_bf16 v[104:107], v[148:151], v[200:203], v[104:107]
	v_mfma_f32_16x16x32_bf16 v[100:103], v[156:159], v[200:203], v[100:103]
	v_mfma_f32_16x16x32_bf16 v[88:91], v[148:151], v[208:211], v[88:91]
	v_mfma_f32_16x16x32_bf16 v[84:87], v[156:159], v[208:211], v[84:87]
	v_mfma_f32_16x16x32_bf16 v[72:75], v[148:151], v[224:227], v[72:75]
	v_mfma_f32_16x16x32_bf16 v[68:71], v[156:159], v[224:227], v[68:71]
	v_mfma_f32_16x16x32_bf16 v[120:123], v[152:155], v[196:199], v[120:123]
	v_mfma_f32_16x16x32_bf16 v[116:119], v[170:173], v[196:199], v[116:119]
	v_mfma_f32_16x16x32_bf16 v[104:107], v[152:155], v[204:207], v[104:107]
	v_mfma_f32_16x16x32_bf16 v[100:103], v[170:173], v[204:207], v[100:103]
	v_mfma_f32_16x16x32_bf16 v[88:91], v[152:155], v[218:221], v[88:91]
	v_mfma_f32_16x16x32_bf16 v[84:87], v[170:173], v[218:221], v[84:87]
	v_mfma_f32_16x16x32_bf16 v[72:75], v[152:155], v[228:231], v[72:75]
	v_mfma_f32_16x16x32_bf16 v[68:71], v[170:173], v[228:231], v[68:71]
	s_setprio 0
	s_barrier
	s_add_i32 s40, s41, s50
	s_mov_b32 m0, s40
	ds_read_b128 v[174:177], v194 offset:16384
	ds_read_b128 v[196:199], v194 offset:17408
	ds_read_b128 v[200:203], v194 offset:18432
	ds_read_b128 v[204:207], v194 offset:19456
	ds_read_b128 v[208:211], v194 offset:20480
	ds_read_b128 v[218:221], v194 offset:21504
	ds_read_b128 v[224:227], v194 offset:22528
	ds_read_b128 v[228:231], v194 offset:23552
	global_load_lds_dwordx4 v162, s[46:47]
	s_add_i32 m0, s40, 0x2000
	s_add_u32 s40, s46, 0x40000
	s_addc_u32 s41, s47, 0
	s_add_i32 s25, s25, s50
	global_load_lds_dwordx4 v0, s[46:47]
	s_mov_b32 m0, s25
	s_nop 0
	global_load_lds_dwordx4 v162, s[40:41]
	s_add_i32 m0, s25, 0x2000
	s_nop 0
	global_load_lds_dwordx4 v0, s[40:41]
	s_mov_b32 m0, s51
	s_nop 0
	global_load_lds_dwordx4 v164, s[48:49]
	s_mov_b32 m0, s52
	s_nop 0
	global_load_lds_dwordx4 v160, s[48:49]
	s_waitcnt vmcnt(8)
	s_waitcnt lgkmcnt(0)
	s_barrier
	s_setprio 1
	s_waitcnt lgkmcnt(0)
	v_mfma_f32_16x16x32_bf16 v[64:67], v[132:135], v[174:177], v[64:67]
	v_mfma_f32_16x16x32_bf16 v[60:63], v[140:143], v[174:177], v[60:63]
	v_mfma_f32_16x16x32_bf16 v[48:51], v[132:135], v[200:203], v[48:51]
	v_mfma_f32_16x16x32_bf16 v[44:47], v[140:143], v[200:203], v[44:47]
	v_mfma_f32_16x16x32_bf16 v[32:35], v[132:135], v[208:211], v[32:35]
	v_mfma_f32_16x16x32_bf16 v[28:31], v[140:143], v[208:211], v[28:31]
	v_mfma_f32_16x16x32_bf16 v[16:19], v[132:135], v[224:227], v[16:19]
	v_mfma_f32_16x16x32_bf16 v[12:15], v[140:143], v[224:227], v[12:15]
	v_mfma_f32_16x16x32_bf16 v[64:67], v[136:139], v[196:199], v[64:67]
	v_mfma_f32_16x16x32_bf16 v[60:63], v[144:147], v[196:199], v[60:63]
	v_mfma_f32_16x16x32_bf16 v[48:51], v[136:139], v[204:207], v[48:51]
	v_mfma_f32_16x16x32_bf16 v[44:47], v[144:147], v[204:207], v[44:47]
	v_mfma_f32_16x16x32_bf16 v[32:35], v[136:139], v[218:221], v[32:35]
	v_mfma_f32_16x16x32_bf16 v[28:31], v[144:147], v[218:221], v[28:31]
	v_mfma_f32_16x16x32_bf16 v[16:19], v[136:139], v[228:231], v[16:19]
	v_mfma_f32_16x16x32_bf16 v[12:15], v[144:147], v[228:231], v[12:15]
	s_setprio 0
	s_setprio 1
	v_mfma_f32_16x16x32_bf16 v[56:59], v[148:151], v[174:177], v[56:59]
	v_mfma_f32_16x16x32_bf16 v[52:55], v[156:159], v[174:177], v[52:55]
	v_mfma_f32_16x16x32_bf16 v[40:43], v[148:151], v[200:203], v[40:43]
	v_mfma_f32_16x16x32_bf16 v[36:39], v[156:159], v[200:203], v[36:39]
	v_mfma_f32_16x16x32_bf16 v[24:27], v[148:151], v[208:211], v[24:27]
	v_mfma_f32_16x16x32_bf16 v[20:23], v[156:159], v[208:211], v[20:23]
	v_mfma_f32_16x16x32_bf16 v[8:11], v[148:151], v[224:227], v[8:11]
	v_mfma_f32_16x16x32_bf16 v[4:7], v[156:159], v[224:227], v[4:7]
	v_mfma_f32_16x16x32_bf16 v[56:59], v[152:155], v[196:199], v[56:59]
	v_mfma_f32_16x16x32_bf16 v[52:55], v[170:173], v[196:199], v[52:55]
	v_mfma_f32_16x16x32_bf16 v[40:43], v[152:155], v[204:207], v[40:43]
	v_mfma_f32_16x16x32_bf16 v[36:39], v[170:173], v[204:207], v[36:39]
	v_mfma_f32_16x16x32_bf16 v[24:27], v[152:155], v[218:221], v[24:27]
	v_mfma_f32_16x16x32_bf16 v[20:23], v[170:173], v[218:221], v[20:23]
	v_mfma_f32_16x16x32_bf16 v[8:11], v[152:155], v[228:231], v[8:11]
	v_mfma_f32_16x16x32_bf16 v[4:7], v[170:173], v[228:231], v[4:7]
	s_setprio 0
	s_barrier
	s_add_i32 s25, 0, 0x18000
	s_add_i32 s70, 0, 0x1c000
	v_add_u32_e32 v144, s25, v187
	v_add_u32_e32 v170, s70, v187
	ds_read_b128 v[132:135], v144
	ds_read_b128 v[136:139], v144 offset:1024
	ds_read_b128 v[140:143], v144 offset:2048
	ds_read_b128 v[144:147], v144 offset:3072
	ds_read_b128 v[148:151], v170
	ds_read_b128 v[152:155], v170 offset:1024
	ds_read_b128 v[156:159], v170 offset:2048
	ds_read_b128 v[170:173], v170 offset:3072
	s_add_u32 s40, s48, 0x40000
	s_addc_u32 s41, s49, 0
	s_mov_b32 m0, s53
	ds_read_b128 v[174:177], v194 offset:32768
	ds_read_b128 v[196:199], v194 offset:33792
	ds_read_b128 v[200:203], v194 offset:34816
	ds_read_b128 v[204:207], v194 offset:35840
	ds_read_b128 v[208:211], v194 offset:36864
	ds_read_b128 v[218:221], v194 offset:37888
	ds_read_b128 v[224:227], v194 offset:38912
	ds_read_b128 v[228:231], v194 offset:39936
	global_load_lds_dwordx4 v164, s[40:41]
	s_mov_b32 m0, s54
	s_nop 0
	global_load_lds_dwordx4 v160, s[40:41]
	s_waitcnt vmcnt(8)
	s_waitcnt lgkmcnt(0)
	s_barrier
	s_setprio 1
	s_waitcnt lgkmcnt(0)
	v_mfma_f32_16x16x32_bf16 v[128:131], v[132:135], v[174:177], v[128:131]
	v_mfma_f32_16x16x32_bf16 v[124:127], v[140:143], v[174:177], v[124:127]
	v_mfma_f32_16x16x32_bf16 v[112:115], v[132:135], v[200:203], v[112:115]
	v_mfma_f32_16x16x32_bf16 v[108:111], v[140:143], v[200:203], v[108:111]
	v_mfma_f32_16x16x32_bf16 v[96:99], v[132:135], v[208:211], v[96:99]
	v_mfma_f32_16x16x32_bf16 v[92:95], v[140:143], v[208:211], v[92:95]
	v_mfma_f32_16x16x32_bf16 v[80:83], v[132:135], v[224:227], v[80:83]
	v_mfma_f32_16x16x32_bf16 v[76:79], v[140:143], v[224:227], v[76:79]
	v_mfma_f32_16x16x32_bf16 v[128:131], v[136:139], v[196:199], v[128:131]
	v_mfma_f32_16x16x32_bf16 v[124:127], v[144:147], v[196:199], v[124:127]
	v_mfma_f32_16x16x32_bf16 v[112:115], v[136:139], v[204:207], v[112:115]
	v_mfma_f32_16x16x32_bf16 v[108:111], v[144:147], v[204:207], v[108:111]
	v_mfma_f32_16x16x32_bf16 v[96:99], v[136:139], v[218:221], v[96:99]
	v_mfma_f32_16x16x32_bf16 v[92:95], v[144:147], v[218:221], v[92:95]
	v_mfma_f32_16x16x32_bf16 v[80:83], v[136:139], v[228:231], v[80:83]
	v_mfma_f32_16x16x32_bf16 v[76:79], v[144:147], v[228:231], v[76:79]
	s_setprio 0
	s_setprio 1
	v_mfma_f32_16x16x32_bf16 v[120:123], v[148:151], v[174:177], v[120:123]
	v_mfma_f32_16x16x32_bf16 v[116:119], v[156:159], v[174:177], v[116:119]
	v_mfma_f32_16x16x32_bf16 v[104:107], v[148:151], v[200:203], v[104:107]
	v_mfma_f32_16x16x32_bf16 v[100:103], v[156:159], v[200:203], v[100:103]
	v_mfma_f32_16x16x32_bf16 v[88:91], v[148:151], v[208:211], v[88:91]
	v_mfma_f32_16x16x32_bf16 v[84:87], v[156:159], v[208:211], v[84:87]
	v_mfma_f32_16x16x32_bf16 v[72:75], v[148:151], v[224:227], v[72:75]
	v_mfma_f32_16x16x32_bf16 v[68:71], v[156:159], v[224:227], v[68:71]
	v_mfma_f32_16x16x32_bf16 v[120:123], v[152:155], v[196:199], v[120:123]
	v_mfma_f32_16x16x32_bf16 v[116:119], v[170:173], v[196:199], v[116:119]
	v_mfma_f32_16x16x32_bf16 v[104:107], v[152:155], v[204:207], v[104:107]
	v_mfma_f32_16x16x32_bf16 v[100:103], v[170:173], v[204:207], v[100:103]
	v_mfma_f32_16x16x32_bf16 v[88:91], v[152:155], v[218:221], v[88:91]
	v_mfma_f32_16x16x32_bf16 v[84:87], v[170:173], v[218:221], v[84:87]
	v_mfma_f32_16x16x32_bf16 v[72:75], v[152:155], v[228:231], v[72:75]
	v_mfma_f32_16x16x32_bf16 v[68:71], v[170:173], v[228:231], v[68:71]
	s_setprio 0
	s_barrier
	s_add_i32 s25, s25, s50
	s_mov_b32 m0, s25
	ds_read_b128 v[174:177], v194 offset:49152
	ds_read_b128 v[196:199], v194 offset:50176
	ds_read_b128 v[200:203], v194 offset:51200
	ds_read_b128 v[204:207], v194 offset:52224
	ds_read_b128 v[208:211], v194 offset:53248
	ds_read_b128 v[218:221], v194 offset:54272
	ds_read_b128 v[224:227], v194 offset:55296
	ds_read_b128 v[228:231], v194 offset:56320
	s_add_u32 s100, s46, 0x80
	s_addc_u32 s101, s47, 0
	global_load_lds_dwordx4 v162, s[100:101]
	s_add_i32 m0, s25, 0x2000
	s_add_u32 s40, s46, 0x40080
	s_addc_u32 s41, s47, 0
	s_add_i32 s25, s70, s50
	s_add_u32 s100, s46, 0x80
	s_addc_u32 s101, s47, 0
	global_load_lds_dwordx4 v0, s[100:101]
	s_mov_b32 m0, s25
	s_nop 0
	global_load_lds_dwordx4 v162, s[40:41]
	s_add_i32 m0, s25, 0x2000
	s_nop 0
	global_load_lds_dwordx4 v0, s[40:41]
	s_mov_b32 m0, s55
	s_nop 0
	s_add_u32 s100, s48, 0x80
	s_addc_u32 s101, s49, 0
	global_load_lds_dwordx4 v164, s[100:101]
	s_mov_b32 m0, s58
	s_nop 0
	s_add_u32 s100, s48, 0x80
	s_addc_u32 s101, s49, 0
	global_load_lds_dwordx4 v160, s[100:101]
	s_waitcnt vmcnt(8)
	s_waitcnt lgkmcnt(0)
	s_barrier
	s_setprio 1
	s_waitcnt lgkmcnt(0)
	v_mfma_f32_16x16x32_bf16 v[64:67], v[132:135], v[174:177], v[64:67]
	v_mfma_f32_16x16x32_bf16 v[60:63], v[140:143], v[174:177], v[60:63]
	v_mfma_f32_16x16x32_bf16 v[48:51], v[132:135], v[200:203], v[48:51]
	v_mfma_f32_16x16x32_bf16 v[44:47], v[140:143], v[200:203], v[44:47]
	v_mfma_f32_16x16x32_bf16 v[32:35], v[132:135], v[208:211], v[32:35]
	v_mfma_f32_16x16x32_bf16 v[28:31], v[140:143], v[208:211], v[28:31]
	v_mfma_f32_16x16x32_bf16 v[16:19], v[132:135], v[224:227], v[16:19]
	v_mfma_f32_16x16x32_bf16 v[12:15], v[140:143], v[224:227], v[12:15]
	v_mfma_f32_16x16x32_bf16 v[64:67], v[136:139], v[196:199], v[64:67]
	v_mfma_f32_16x16x32_bf16 v[60:63], v[144:147], v[196:199], v[60:63]
	v_mfma_f32_16x16x32_bf16 v[48:51], v[136:139], v[204:207], v[48:51]
	v_mfma_f32_16x16x32_bf16 v[44:47], v[144:147], v[204:207], v[44:47]
	v_mfma_f32_16x16x32_bf16 v[32:35], v[136:139], v[218:221], v[32:35]
	v_mfma_f32_16x16x32_bf16 v[28:31], v[144:147], v[218:221], v[28:31]
	v_mfma_f32_16x16x32_bf16 v[16:19], v[136:139], v[228:231], v[16:19]
	v_mfma_f32_16x16x32_bf16 v[12:15], v[144:147], v[228:231], v[12:15]
	s_setprio 0
	s_setprio 1
	v_mfma_f32_16x16x32_bf16 v[56:59], v[148:151], v[174:177], v[56:59]
	v_mfma_f32_16x16x32_bf16 v[52:55], v[156:159], v[174:177], v[52:55]
	v_mfma_f32_16x16x32_bf16 v[40:43], v[148:151], v[200:203], v[40:43]
	v_mfma_f32_16x16x32_bf16 v[36:39], v[156:159], v[200:203], v[36:39]
	v_mfma_f32_16x16x32_bf16 v[24:27], v[148:151], v[208:211], v[24:27]
	v_mfma_f32_16x16x32_bf16 v[20:23], v[156:159], v[208:211], v[20:23]
	v_mfma_f32_16x16x32_bf16 v[8:11], v[148:151], v[224:227], v[8:11]
	v_mfma_f32_16x16x32_bf16 v[4:7], v[156:159], v[224:227], v[4:7]
	v_mfma_f32_16x16x32_bf16 v[56:59], v[152:155], v[196:199], v[56:59]
	v_mfma_f32_16x16x32_bf16 v[52:55], v[170:173], v[196:199], v[52:55]
	v_mfma_f32_16x16x32_bf16 v[40:43], v[152:155], v[204:207], v[40:43]
	v_mfma_f32_16x16x32_bf16 v[36:39], v[170:173], v[204:207], v[36:39]
	v_mfma_f32_16x16x32_bf16 v[24:27], v[152:155], v[218:221], v[24:27]
	v_mfma_f32_16x16x32_bf16 v[20:23], v[170:173], v[218:221], v[20:23]
	v_mfma_f32_16x16x32_bf16 v[8:11], v[152:155], v[228:231], v[8:11]
	v_mfma_f32_16x16x32_bf16 v[4:7], v[170:173], v[228:231], v[4:7]
	s_setprio 0
	s_barrier
	s_add_i32 s88, s88, 2
	s_add_u32 s44, s44, 0x100
	s_addc_u32 s45, s45, 0
	s_add_u32 s68, s68, 0x100
	s_addc_u32 s69, s69, 0
	s_cmp_gt_u32 s88, 13
	s_cbranch_scc0 .LBB0_334
	s_and_b64 vcc, exec, s[12:13]
	s_cbranch_vccz .LBB0_337
	s_barrier

.LBB0_595:
	s_add_u32 s36, s26, 0x100
	s_addc_u32 s37, s27, 0
	s_add_i32 s40, 0, 0x10000
	s_cmp_eq_u32 s89, 40
	s_cselect_b32 s47, s9, s37
	s_cselect_b32 s46, s8, s36
	s_cselect_b32 s45, s19, s88
	s_cselect_b32 s44, s18, s69
	s_add_i32 s41, 0, 0x14000
	v_add_u32_e32 v144, s40, v170
	v_add_u32_e32 v168, s41, v170
	ds_read_b128 v[132:135], v144
	ds_read_b128 v[136:139], v144 offset:1024
	ds_read_b128 v[140:143], v144 offset:2048
	ds_read_b128 v[144:147], v144 offset:3072
	ds_read_b128 v[148:151], v168
	ds_read_b128 v[160:163], v168 offset:1024
	ds_read_b128 v[164:167], v168 offset:2048
	ds_read_b128 v[174:177], v168 offset:3072
	s_add_i32 m0, s49, 0xc000
	ds_read_b128 v[190:193], v172
	ds_read_b128 v[194:197], v172 offset:1024
	ds_read_b128 v[198:201], v172 offset:2048
	ds_read_b128 v[202:205], v172 offset:3072
	ds_read_b128 v[206:209], v172 offset:4096
	ds_read_b128 v[218:221], v172 offset:5120
	ds_read_b128 v[224:227], v172 offset:6144
	ds_read_b128 v[228:231], v172 offset:7168
	global_load_lds_dwordx4 v156, s[26:27]
	s_add_i32 m0, s49, 0xe000
	s_nop 0
	global_load_lds_dwordx4 v158, s[26:27]
	s_waitcnt vmcnt(8)
	s_waitcnt lgkmcnt(0)
	s_barrier
	s_setprio 1
	s_waitcnt lgkmcnt(0)
	v_mfma_f32_16x16x32_bf16 v[128:131], v[132:135], v[190:193], v[128:131]
	v_mfma_f32_16x16x32_bf16 v[124:127], v[140:143], v[190:193], v[124:127]
	v_mfma_f32_16x16x32_bf16 v[120:123], v[132:135], v[198:201], v[120:123]
	v_mfma_f32_16x16x32_bf16 v[116:119], v[140:143], v[198:201], v[116:119]
	v_mfma_f32_16x16x32_bf16 v[96:99], v[132:135], v[206:209], v[96:99]
	v_mfma_f32_16x16x32_bf16 v[92:95], v[140:143], v[206:209], v[92:95]
	v_mfma_f32_16x16x32_bf16 v[84:87], v[132:135], v[224:227], v[84:87]
	v_mfma_f32_16x16x32_bf16 v[76:79], v[140:143], v[224:227], v[76:79]
	v_mfma_f32_16x16x32_bf16 v[128:131], v[136:139], v[194:197], v[128:131]
	v_mfma_f32_16x16x32_bf16 v[124:127], v[144:147], v[194:197], v[124:127]
	v_mfma_f32_16x16x32_bf16 v[120:123], v[136:139], v[202:205], v[120:123]
	v_mfma_f32_16x16x32_bf16 v[116:119], v[144:147], v[202:205], v[116:119]
	v_mfma_f32_16x16x32_bf16 v[96:99], v[136:139], v[218:221], v[96:99]
	v_mfma_f32_16x16x32_bf16 v[92:95], v[144:147], v[218:221], v[92:95]
	v_mfma_f32_16x16x32_bf16 v[84:87], v[136:139], v[228:231], v[84:87]
	v_mfma_f32_16x16x32_bf16 v[76:79], v[144:147], v[228:231], v[76:79]
	s_setprio 0
	s_setprio 1
	v_mfma_f32_16x16x32_bf16 v[112:115], v[148:151], v[190:193], v[112:115]
	v_mfma_f32_16x16x32_bf16 v[108:111], v[164:167], v[190:193], v[108:111]
	v_mfma_f32_16x16x32_bf16 v[104:107], v[148:151], v[198:201], v[104:107]
	v_mfma_f32_16x16x32_bf16 v[100:103], v[164:167], v[198:201], v[100:103]
	v_mfma_f32_16x16x32_bf16 v[88:91], v[148:151], v[206:209], v[88:91]
	v_mfma_f32_16x16x32_bf16 v[80:83], v[164:167], v[206:209], v[80:83]
	v_mfma_f32_16x16x32_bf16 v[72:75], v[148:151], v[224:227], v[72:75]
	v_mfma_f32_16x16x32_bf16 v[68:71], v[164:167], v[224:227], v[68:71]
	v_mfma_f32_16x16x32_bf16 v[112:115], v[160:163], v[194:197], v[112:115]
	v_mfma_f32_16x16x32_bf16 v[108:111], v[174:177], v[194:197], v[108:111]
	v_mfma_f32_16x16x32_bf16 v[104:107], v[160:163], v[202:205], v[104:107]
	v_mfma_f32_16x16x32_bf16 v[100:103], v[174:177], v[202:205], v[100:103]
	v_mfma_f32_16x16x32_bf16 v[88:91], v[160:163], v[218:221], v[88:91]
	v_mfma_f32_16x16x32_bf16 v[80:83], v[174:177], v[218:221], v[80:83]
	v_mfma_f32_16x16x32_bf16 v[72:75], v[160:163], v[228:231], v[72:75]
	v_mfma_f32_16x16x32_bf16 v[68:71], v[174:177], v[228:231], v[68:71]
	s_setprio 0
	s_barrier
	s_add_i32 s26, s40, s48
	s_mov_b32 m0, s26
	ds_read_b128 v[190:193], v172 offset:16384
	ds_read_b128 v[194:197], v172 offset:17408
	ds_read_b128 v[198:201], v172 offset:18432
	ds_read_b128 v[202:205], v172 offset:19456
	ds_read_b128 v[206:209], v172 offset:20480
	ds_read_b128 v[218:221], v172 offset:21504
	ds_read_b128 v[224:227], v172 offset:22528
	ds_read_b128 v[228:231], v172 offset:23552
	global_load_lds_dwordx4 v180, s[44:45]
	s_add_i32 m0, s26, 0x2000
	s_add_u32 s26, s44, 0xb0000
	s_addc_u32 s27, s45, 0
	s_add_i32 s40, s41, s48
	global_load_lds_dwordx4 v0, s[44:45]
	s_mov_b32 m0, s40
	s_nop 0
	global_load_lds_dwordx4 v180, s[26:27]
	s_add_i32 m0, s40, 0x2000
	s_nop 0
	global_load_lds_dwordx4 v0, s[26:27]
	s_mov_b32 m0, s49
	s_nop 0
	global_load_lds_dwordx4 v154, s[46:47]
	s_mov_b32 m0, s50
	s_nop 0
	global_load_lds_dwordx4 v152, s[46:47]
	s_waitcnt vmcnt(8)
	s_waitcnt lgkmcnt(0)
	s_barrier
	s_setprio 1
	s_waitcnt lgkmcnt(0)
	v_mfma_f32_16x16x32_bf16 v[64:67], v[132:135], v[190:193], v[64:67]
	v_mfma_f32_16x16x32_bf16 v[60:63], v[140:143], v[190:193], v[60:63]
	v_mfma_f32_16x16x32_bf16 v[52:55], v[132:135], v[198:201], v[52:55]
	v_mfma_f32_16x16x32_bf16 v[44:47], v[140:143], v[198:201], v[44:47]
	v_mfma_f32_16x16x32_bf16 v[36:39], v[132:135], v[206:209], v[36:39]
	v_mfma_f32_16x16x32_bf16 v[28:31], v[140:143], v[206:209], v[28:31]
	v_mfma_f32_16x16x32_bf16 v[20:23], v[132:135], v[224:227], v[20:23]
	v_mfma_f32_16x16x32_bf16 v[12:15], v[140:143], v[224:227], v[12:15]
	v_mfma_f32_16x16x32_bf16 v[64:67], v[136:139], v[194:197], v[64:67]
	v_mfma_f32_16x16x32_bf16 v[60:63], v[144:147], v[194:197], v[60:63]
	v_mfma_f32_16x16x32_bf16 v[52:55], v[136:139], v[202:205], v[52:55]
	v_mfma_f32_16x16x32_bf16 v[44:47], v[144:147], v[202:205], v[44:47]
	v_mfma_f32_16x16x32_bf16 v[36:39], v[136:139], v[218:221], v[36:39]
	v_mfma_f32_16x16x32_bf16 v[28:31], v[144:147], v[218:221], v[28:31]
	v_mfma_f32_16x16x32_bf16 v[20:23], v[136:139], v[228:231], v[20:23]
	v_mfma_f32_16x16x32_bf16 v[12:15], v[144:147], v[228:231], v[12:15]
	s_setprio 0
	s_setprio 1
	v_mfma_f32_16x16x32_bf16 v[56:59], v[148:151], v[190:193], v[56:59]
	v_mfma_f32_16x16x32_bf16 v[48:51], v[164:167], v[190:193], v[48:51]
	v_mfma_f32_16x16x32_bf16 v[40:43], v[148:151], v[198:201], v[40:43]
	v_mfma_f32_16x16x32_bf16 v[32:35], v[164:167], v[198:201], v[32:35]
	v_mfma_f32_16x16x32_bf16 v[24:27], v[148:151], v[206:209], v[24:27]
	v_mfma_f32_16x16x32_bf16 v[16:19], v[164:167], v[206:209], v[16:19]
	v_mfma_f32_16x16x32_bf16 v[8:11], v[148:151], v[224:227], v[8:11]
	v_mfma_f32_16x16x32_bf16 v[4:7], v[164:167], v[224:227], v[4:7]
	v_mfma_f32_16x16x32_bf16 v[56:59], v[160:163], v[194:197], v[56:59]
	v_mfma_f32_16x16x32_bf16 v[48:51], v[174:177], v[194:197], v[48:51]
	v_mfma_f32_16x16x32_bf16 v[40:43], v[160:163], v[202:205], v[40:43]
	v_mfma_f32_16x16x32_bf16 v[32:35], v[174:177], v[202:205], v[32:35]
	v_mfma_f32_16x16x32_bf16 v[24:27], v[160:163], v[218:221], v[24:27]
	v_mfma_f32_16x16x32_bf16 v[16:19], v[174:177], v[218:221], v[16:19]
	v_mfma_f32_16x16x32_bf16 v[8:11], v[160:163], v[228:231], v[8:11]
	v_mfma_f32_16x16x32_bf16 v[4:7], v[174:177], v[228:231], v[4:7]
	s_setprio 0
	s_barrier
	s_add_i32 s40, 0, 0x18000
	s_add_i32 s41, 0, 0x1c000
	v_add_u32_e32 v144, s40, v170
	v_add_u32_e32 v173, s41, v170
	ds_read_b128 v[132:135], v144
	ds_read_b128 v[136:139], v144 offset:1024
	ds_read_b128 v[140:143], v144 offset:2048
	ds_read_b128 v[144:147], v144 offset:3072
	ds_read_b128 v[148:151], v173
	ds_read_b128 v[160:163], v173 offset:1024
	ds_read_b128 v[164:167], v173 offset:2048
	ds_read_b128 v[174:177], v173 offset:3072
	s_add_u32 s26, s46, 0xb0000
	s_addc_u32 s27, s47, 0
	s_mov_b32 m0, s51
	ds_read_b128 v[190:193], v172 offset:32768
	ds_read_b128 v[194:197], v172 offset:33792
	ds_read_b128 v[198:201], v172 offset:34816
	ds_read_b128 v[202:205], v172 offset:35840
	ds_read_b128 v[206:209], v172 offset:36864
	ds_read_b128 v[218:221], v172 offset:37888
	ds_read_b128 v[224:227], v172 offset:38912
	ds_read_b128 v[228:231], v172 offset:39936
	global_load_lds_dwordx4 v154, s[26:27]
	s_mov_b32 m0, s53
	s_nop 0
	global_load_lds_dwordx4 v152, s[26:27]
	s_waitcnt vmcnt(8)
	s_waitcnt lgkmcnt(0)
	s_barrier
	s_setprio 1
	s_waitcnt lgkmcnt(0)
	v_mfma_f32_16x16x32_bf16 v[128:131], v[132:135], v[190:193], v[128:131]
	v_mfma_f32_16x16x32_bf16 v[124:127], v[140:143], v[190:193], v[124:127]
	v_mfma_f32_16x16x32_bf16 v[120:123], v[132:135], v[198:201], v[120:123]
	v_mfma_f32_16x16x32_bf16 v[116:119], v[140:143], v[198:201], v[116:119]
	v_mfma_f32_16x16x32_bf16 v[96:99], v[132:135], v[206:209], v[96:99]
	v_mfma_f32_16x16x32_bf16 v[92:95], v[140:143], v[206:209], v[92:95]
	v_mfma_f32_16x16x32_bf16 v[84:87], v[132:135], v[224:227], v[84:87]
	v_mfma_f32_16x16x32_bf16 v[76:79], v[140:143], v[224:227], v[76:79]
	v_mfma_f32_16x16x32_bf16 v[128:131], v[136:139], v[194:197], v[128:131]
	v_mfma_f32_16x16x32_bf16 v[124:127], v[144:147], v[194:197], v[124:127]
	v_mfma_f32_16x16x32_bf16 v[120:123], v[136:139], v[202:205], v[120:123]
	v_mfma_f32_16x16x32_bf16 v[116:119], v[144:147], v[202:205], v[116:119]
	v_mfma_f32_16x16x32_bf16 v[96:99], v[136:139], v[218:221], v[96:99]
	v_mfma_f32_16x16x32_bf16 v[92:95], v[144:147], v[218:221], v[92:95]
	v_mfma_f32_16x16x32_bf16 v[84:87], v[136:139], v[228:231], v[84:87]
	v_mfma_f32_16x16x32_bf16 v[76:79], v[144:147], v[228:231], v[76:79]
	s_setprio 0
	s_setprio 1
	v_mfma_f32_16x16x32_bf16 v[112:115], v[148:151], v[190:193], v[112:115]
	v_mfma_f32_16x16x32_bf16 v[108:111], v[164:167], v[190:193], v[108:111]
	v_mfma_f32_16x16x32_bf16 v[104:107], v[148:151], v[198:201], v[104:107]
	v_mfma_f32_16x16x32_bf16 v[100:103], v[164:167], v[198:201], v[100:103]
	v_mfma_f32_16x16x32_bf16 v[88:91], v[148:151], v[206:209], v[88:91]
	v_mfma_f32_16x16x32_bf16 v[80:83], v[164:167], v[206:209], v[80:83]
	v_mfma_f32_16x16x32_bf16 v[72:75], v[148:151], v[224:227], v[72:75]
	v_mfma_f32_16x16x32_bf16 v[68:71], v[164:167], v[224:227], v[68:71]
	v_mfma_f32_16x16x32_bf16 v[112:115], v[160:163], v[194:197], v[112:115]
	v_mfma_f32_16x16x32_bf16 v[108:111], v[174:177], v[194:197], v[108:111]
	v_mfma_f32_16x16x32_bf16 v[104:107], v[160:163], v[202:205], v[104:107]
	v_mfma_f32_16x16x32_bf16 v[100:103], v[174:177], v[202:205], v[100:103]
	v_mfma_f32_16x16x32_bf16 v[88:91], v[160:163], v[218:221], v[88:91]
	v_mfma_f32_16x16x32_bf16 v[80:83], v[174:177], v[218:221], v[80:83]
	v_mfma_f32_16x16x32_bf16 v[72:75], v[160:163], v[228:231], v[72:75]
	v_mfma_f32_16x16x32_bf16 v[68:71], v[174:177], v[228:231], v[68:71]
	s_setprio 0
	s_barrier
	s_add_i32 s26, s40, s48
	s_mov_b32 m0, s26
	ds_read_b128 v[190:193], v172 offset:49152
	ds_read_b128 v[194:197], v172 offset:50176
	ds_read_b128 v[198:201], v172 offset:51200
	ds_read_b128 v[202:205], v172 offset:52224
	ds_read_b128 v[206:209], v172 offset:53248
	ds_read_b128 v[218:221], v172 offset:54272
	ds_read_b128 v[224:227], v172 offset:55296
	ds_read_b128 v[228:231], v172 offset:56320
	s_add_u32 s100, s44, 0x80
	s_addc_u32 s101, s45, 0
	global_load_lds_dwordx4 v180, s[100:101]
	s_add_i32 m0, s26, 0x2000
	s_add_u32 s26, s44, 0xb0080
	s_addc_u32 s27, s45, 0
	s_add_i32 s40, s41, s48
	s_add_u32 s100, s44, 0x80
	s_addc_u32 s101, s45, 0
	global_load_lds_dwordx4 v0, s[100:101]
	s_mov_b32 m0, s40
	s_nop 0
	global_load_lds_dwordx4 v180, s[26:27]
	s_add_i32 m0, s40, 0x2000
	s_nop 0
	global_load_lds_dwordx4 v0, s[26:27]
	s_mov_b32 m0, s54
	s_nop 0
	s_add_u32 s100, s46, 0x80
	s_addc_u32 s101, s47, 0
	global_load_lds_dwordx4 v154, s[100:101]
	s_mov_b32 m0, s55
	s_nop 0
	s_add_u32 s100, s46, 0x80
	s_addc_u32 s101, s47, 0
	global_load_lds_dwordx4 v152, s[100:101]
	s_waitcnt vmcnt(8)
	s_waitcnt lgkmcnt(0)
	s_barrier
	s_setprio 1
	s_waitcnt lgkmcnt(0)
	v_mfma_f32_16x16x32_bf16 v[64:67], v[132:135], v[190:193], v[64:67]
	v_mfma_f32_16x16x32_bf16 v[60:63], v[140:143], v[190:193], v[60:63]
	v_mfma_f32_16x16x32_bf16 v[52:55], v[132:135], v[198:201], v[52:55]
	v_mfma_f32_16x16x32_bf16 v[44:47], v[140:143], v[198:201], v[44:47]
	v_mfma_f32_16x16x32_bf16 v[36:39], v[132:135], v[206:209], v[36:39]
	v_mfma_f32_16x16x32_bf16 v[28:31], v[140:143], v[206:209], v[28:31]
	v_mfma_f32_16x16x32_bf16 v[20:23], v[132:135], v[224:227], v[20:23]
	v_mfma_f32_16x16x32_bf16 v[12:15], v[140:143], v[224:227], v[12:15]
	v_mfma_f32_16x16x32_bf16 v[64:67], v[136:139], v[194:197], v[64:67]
	v_mfma_f32_16x16x32_bf16 v[60:63], v[144:147], v[194:197], v[60:63]
	v_mfma_f32_16x16x32_bf16 v[52:55], v[136:139], v[202:205], v[52:55]
	v_mfma_f32_16x16x32_bf16 v[44:47], v[144:147], v[202:205], v[44:47]
	v_mfma_f32_16x16x32_bf16 v[36:39], v[136:139], v[218:221], v[36:39]
	v_mfma_f32_16x16x32_bf16 v[28:31], v[144:147], v[218:221], v[28:31]
	v_mfma_f32_16x16x32_bf16 v[20:23], v[136:139], v[228:231], v[20:23]
	v_mfma_f32_16x16x32_bf16 v[12:15], v[144:147], v[228:231], v[12:15]
	s_setprio 0
	s_setprio 1
	v_mfma_f32_16x16x32_bf16 v[56:59], v[148:151], v[190:193], v[56:59]
	v_mfma_f32_16x16x32_bf16 v[48:51], v[164:167], v[190:193], v[48:51]
	v_mfma_f32_16x16x32_bf16 v[40:43], v[148:151], v[198:201], v[40:43]
	v_mfma_f32_16x16x32_bf16 v[32:35], v[164:167], v[198:201], v[32:35]
	v_mfma_f32_16x16x32_bf16 v[24:27], v[148:151], v[206:209], v[24:27]
	v_mfma_f32_16x16x32_bf16 v[16:19], v[164:167], v[206:209], v[16:19]
	v_mfma_f32_16x16x32_bf16 v[8:11], v[148:151], v[224:227], v[8:11]
	v_mfma_f32_16x16x32_bf16 v[4:7], v[164:167], v[224:227], v[4:7]
	v_mfma_f32_16x16x32_bf16 v[56:59], v[160:163], v[194:197], v[56:59]
	v_mfma_f32_16x16x32_bf16 v[48:51], v[174:177], v[194:197], v[48:51]
	v_mfma_f32_16x16x32_bf16 v[40:43], v[160:163], v[202:205], v[40:43]
	v_mfma_f32_16x16x32_bf16 v[32:35], v[174:177], v[202:205], v[32:35]
	v_mfma_f32_16x16x32_bf16 v[24:27], v[160:163], v[218:221], v[24:27]
	v_mfma_f32_16x16x32_bf16 v[16:19], v[174:177], v[218:221], v[16:19]
	v_mfma_f32_16x16x32_bf16 v[8:11], v[160:163], v[228:231], v[8:11]
	v_mfma_f32_16x16x32_bf16 v[4:7], v[174:177], v[228:231], v[4:7]
	s_setprio 0
	s_barrier
	s_add_i32 s89, s89, 2
	s_add_u32 s69, s69, 0x100
	s_addc_u32 s88, s88, 0
	s_cmp_gt_u32 s89, 41
	s_mov_b64 s[26:27], s[36:37]
	s_cbranch_scc0 .LBB0_595
	s_and_b64 vcc, exec, s[16:17]
	s_cbranch_vccz .LBB0_598
	s_barrier

.LBB0_624:
	s_add_u32 s46, s44, 0x100
	s_addc_u32 s47, s45, 0
	s_add_i32 s40, 0, 0x10000
	s_cmp_eq_u32 s97, 40
	s_cselect_b32 s51, s13, s47
	s_cselect_b32 s50, s12, s46
	s_cselect_b32 s49, s37, s90
	s_cselect_b32 s48, s36, s89
	s_add_i32 s70, 0, 0x14000
	v_add_u32_e32 v144, s40, v187
	v_add_u32_e32 v170, s70, v187
	ds_read_b128 v[132:135], v144
	ds_read_b128 v[136:139], v144 offset:1024
	ds_read_b128 v[140:143], v144 offset:2048
	ds_read_b128 v[144:147], v144 offset:3072
	ds_read_b128 v[148:151], v170
	ds_read_b128 v[152:155], v170 offset:1024
	ds_read_b128 v[156:159], v170 offset:2048
	ds_read_b128 v[170:173], v170 offset:3072
	s_add_i32 m0, s54, 0xc000
	ds_read_b128 v[174:177], v194
	ds_read_b128 v[196:199], v194 offset:1024
	ds_read_b128 v[200:203], v194 offset:2048
	ds_read_b128 v[204:207], v194 offset:3072
	ds_read_b128 v[208:211], v194 offset:4096
	ds_read_b128 v[218:221], v194 offset:5120
	ds_read_b128 v[224:227], v194 offset:6144
	ds_read_b128 v[228:231], v194 offset:7168
	global_load_lds_dwordx4 v166, s[44:45]
	s_add_i32 m0, s54, 0xe000
	s_nop 0
	global_load_lds_dwordx4 v168, s[44:45]
	s_waitcnt vmcnt(8)
	s_waitcnt lgkmcnt(0)
	s_barrier
	s_setprio 1
	s_waitcnt lgkmcnt(0)
	v_mfma_f32_16x16x32_bf16 v[128:131], v[132:135], v[174:177], v[128:131]
	v_mfma_f32_16x16x32_bf16 v[124:127], v[140:143], v[174:177], v[124:127]
	v_mfma_f32_16x16x32_bf16 v[112:115], v[132:135], v[200:203], v[112:115]
	v_mfma_f32_16x16x32_bf16 v[108:111], v[140:143], v[200:203], v[108:111]
	v_mfma_f32_16x16x32_bf16 v[96:99], v[132:135], v[208:211], v[96:99]
	v_mfma_f32_16x16x32_bf16 v[92:95], v[140:143], v[208:211], v[92:95]
	v_mfma_f32_16x16x32_bf16 v[80:83], v[132:135], v[224:227], v[80:83]
	v_mfma_f32_16x16x32_bf16 v[76:79], v[140:143], v[224:227], v[76:79]
	v_mfma_f32_16x16x32_bf16 v[128:131], v[136:139], v[196:199], v[128:131]
	v_mfma_f32_16x16x32_bf16 v[124:127], v[144:147], v[196:199], v[124:127]
	v_mfma_f32_16x16x32_bf16 v[112:115], v[136:139], v[204:207], v[112:115]
	v_mfma_f32_16x16x32_bf16 v[108:111], v[144:147], v[204:207], v[108:111]
	v_mfma_f32_16x16x32_bf16 v[96:99], v[136:139], v[218:221], v[96:99]
	v_mfma_f32_16x16x32_bf16 v[92:95], v[144:147], v[218:221], v[92:95]
	v_mfma_f32_16x16x32_bf16 v[80:83], v[136:139], v[228:231], v[80:83]
	v_mfma_f32_16x16x32_bf16 v[76:79], v[144:147], v[228:231], v[76:79]
	s_setprio 0
	s_setprio 1
	v_mfma_f32_16x16x32_bf16 v[120:123], v[148:151], v[174:177], v[120:123]
	v_mfma_f32_16x16x32_bf16 v[116:119], v[156:159], v[174:177], v[116:119]
	v_mfma_f32_16x16x32_bf16 v[104:107], v[148:151], v[200:203], v[104:107]
	v_mfma_f32_16x16x32_bf16 v[100:103], v[156:159], v[200:203], v[100:103]
	v_mfma_f32_16x16x32_bf16 v[88:91], v[148:151], v[208:211], v[88:91]
	v_mfma_f32_16x16x32_bf16 v[84:87], v[156:159], v[208:211], v[84:87]
	v_mfma_f32_16x16x32_bf16 v[72:75], v[148:151], v[224:227], v[72:75]
	v_mfma_f32_16x16x32_bf16 v[68:71], v[156:159], v[224:227], v[68:71]
	v_mfma_f32_16x16x32_bf16 v[120:123], v[152:155], v[196:199], v[120:123]
	v_mfma_f32_16x16x32_bf16 v[116:119], v[170:173], v[196:199], v[116:119]
	v_mfma_f32_16x16x32_bf16 v[104:107], v[152:155], v[204:207], v[104:107]
	v_mfma_f32_16x16x32_bf16 v[100:103], v[170:173], v[204:207], v[100:103]
	v_mfma_f32_16x16x32_bf16 v[88:91], v[152:155], v[218:221], v[88:91]
	v_mfma_f32_16x16x32_bf16 v[84:87], v[170:173], v[218:221], v[84:87]
	v_mfma_f32_16x16x32_bf16 v[72:75], v[152:155], v[228:231], v[72:75]
	v_mfma_f32_16x16x32_bf16 v[68:71], v[170:173], v[228:231], v[68:71]
	s_setprio 0
	s_barrier
	s_add_i32 s40, s40, s53
	s_mov_b32 m0, s40
	ds_read_b128 v[174:177], v194 offset:16384
	ds_read_b128 v[196:199], v194 offset:17408
	ds_read_b128 v[200:203], v194 offset:18432
	ds_read_b128 v[204:207], v194 offset:19456
	ds_read_b128 v[208:211], v194 offset:20480
	ds_read_b128 v[218:221], v194 offset:21504
	ds_read_b128 v[224:227], v194 offset:22528
	ds_read_b128 v[228:231], v194 offset:23552
	global_load_lds_dwordx4 v162, s[48:49]
	s_add_i32 m0, s40, 0x2000
	s_add_u32 s40, s48, 0xb0000
	s_addc_u32 s41, s49, 0
	s_add_i32 s44, s70, s53
	global_load_lds_dwordx4 v0, s[48:49]
	s_mov_b32 m0, s44
	s_nop 0
	global_load_lds_dwordx4 v162, s[40:41]
	s_add_i32 m0, s44, 0x2000
	s_nop 0
	global_load_lds_dwordx4 v0, s[40:41]
	s_mov_b32 m0, s54
	s_nop 0
	global_load_lds_dwordx4 v164, s[50:51]
	s_mov_b32 m0, s55
	s_nop 0
	global_load_lds_dwordx4 v160, s[50:51]
	s_waitcnt vmcnt(8)
	s_waitcnt lgkmcnt(0)
	s_barrier
	s_setprio 1
	s_waitcnt lgkmcnt(0)
	v_mfma_f32_16x16x32_bf16 v[64:67], v[132:135], v[174:177], v[64:67]
	v_mfma_f32_16x16x32_bf16 v[60:63], v[140:143], v[174:177], v[60:63]
	v_mfma_f32_16x16x32_bf16 v[48:51], v[132:135], v[200:203], v[48:51]
	v_mfma_f32_16x16x32_bf16 v[44:47], v[140:143], v[200:203], v[44:47]
	v_mfma_f32_16x16x32_bf16 v[32:35], v[132:135], v[208:211], v[32:35]
	v_mfma_f32_16x16x32_bf16 v[28:31], v[140:143], v[208:211], v[28:31]
	v_mfma_f32_16x16x32_bf16 v[16:19], v[132:135], v[224:227], v[16:19]
	v_mfma_f32_16x16x32_bf16 v[12:15], v[140:143], v[224:227], v[12:15]
	v_mfma_f32_16x16x32_bf16 v[64:67], v[136:139], v[196:199], v[64:67]
	v_mfma_f32_16x16x32_bf16 v[60:63], v[144:147], v[196:199], v[60:63]
	v_mfma_f32_16x16x32_bf16 v[48:51], v[136:139], v[204:207], v[48:51]
	v_mfma_f32_16x16x32_bf16 v[44:47], v[144:147], v[204:207], v[44:47]
	v_mfma_f32_16x16x32_bf16 v[32:35], v[136:139], v[218:221], v[32:35]
	v_mfma_f32_16x16x32_bf16 v[28:31], v[144:147], v[218:221], v[28:31]
	v_mfma_f32_16x16x32_bf16 v[16:19], v[136:139], v[228:231], v[16:19]
	v_mfma_f32_16x16x32_bf16 v[12:15], v[144:147], v[228:231], v[12:15]
	s_setprio 0
	s_setprio 1
	v_mfma_f32_16x16x32_bf16 v[56:59], v[148:151], v[174:177], v[56:59]
	v_mfma_f32_16x16x32_bf16 v[52:55], v[156:159], v[174:177], v[52:55]
	v_mfma_f32_16x16x32_bf16 v[40:43], v[148:151], v[200:203], v[40:43]
	v_mfma_f32_16x16x32_bf16 v[36:39], v[156:159], v[200:203], v[36:39]
	v_mfma_f32_16x16x32_bf16 v[24:27], v[148:151], v[208:211], v[24:27]
	v_mfma_f32_16x16x32_bf16 v[20:23], v[156:159], v[208:211], v[20:23]
	v_mfma_f32_16x16x32_bf16 v[8:11], v[148:151], v[224:227], v[8:11]
	v_mfma_f32_16x16x32_bf16 v[4:7], v[156:159], v[224:227], v[4:7]
	v_mfma_f32_16x16x32_bf16 v[56:59], v[152:155], v[196:199], v[56:59]
	v_mfma_f32_16x16x32_bf16 v[52:55], v[170:173], v[196:199], v[52:55]
	v_mfma_f32_16x16x32_bf16 v[40:43], v[152:155], v[204:207], v[40:43]
	v_mfma_f32_16x16x32_bf16 v[36:39], v[170:173], v[204:207], v[36:39]
	v_mfma_f32_16x16x32_bf16 v[24:27], v[152:155], v[218:221], v[24:27]
	v_mfma_f32_16x16x32_bf16 v[20:23], v[170:173], v[218:221], v[20:23]
	v_mfma_f32_16x16x32_bf16 v[8:11], v[152:155], v[228:231], v[8:11]
	v_mfma_f32_16x16x32_bf16 v[4:7], v[170:173], v[228:231], v[4:7]
	s_setprio 0
	s_barrier
	s_add_i32 s44, 0, 0x18000
	s_add_i32 s45, 0, 0x1c000
	v_add_u32_e32 v144, s44, v187
	v_add_u32_e32 v170, s45, v187
	ds_read_b128 v[132:135], v144
	ds_read_b128 v[136:139], v144 offset:1024
	ds_read_b128 v[140:143], v144 offset:2048
	ds_read_b128 v[144:147], v144 offset:3072
	ds_read_b128 v[148:151], v170
	ds_read_b128 v[152:155], v170 offset:1024
	ds_read_b128 v[156:159], v170 offset:2048
	ds_read_b128 v[170:173], v170 offset:3072
	s_add_u32 s40, s50, 0xb0000
	s_addc_u32 s41, s51, 0
	s_mov_b32 m0, s58
	ds_read_b128 v[174:177], v194 offset:32768
	ds_read_b128 v[196:199], v194 offset:33792
	ds_read_b128 v[200:203], v194 offset:34816
	ds_read_b128 v[204:207], v194 offset:35840
	ds_read_b128 v[208:211], v194 offset:36864
	ds_read_b128 v[218:221], v194 offset:37888
	ds_read_b128 v[224:227], v194 offset:38912
	ds_read_b128 v[228:231], v194 offset:39936
	global_load_lds_dwordx4 v164, s[40:41]
	s_mov_b32 m0, s59
	s_nop 0
	global_load_lds_dwordx4 v160, s[40:41]
	s_waitcnt vmcnt(8)
	s_waitcnt lgkmcnt(0)
	s_barrier
	s_setprio 1
	s_waitcnt lgkmcnt(0)
	v_mfma_f32_16x16x32_bf16 v[128:131], v[132:135], v[174:177], v[128:131]
	v_mfma_f32_16x16x32_bf16 v[124:127], v[140:143], v[174:177], v[124:127]
	v_mfma_f32_16x16x32_bf16 v[112:115], v[132:135], v[200:203], v[112:115]
	v_mfma_f32_16x16x32_bf16 v[108:111], v[140:143], v[200:203], v[108:111]
	v_mfma_f32_16x16x32_bf16 v[96:99], v[132:135], v[208:211], v[96:99]
	v_mfma_f32_16x16x32_bf16 v[92:95], v[140:143], v[208:211], v[92:95]
	v_mfma_f32_16x16x32_bf16 v[80:83], v[132:135], v[224:227], v[80:83]
	v_mfma_f32_16x16x32_bf16 v[76:79], v[140:143], v[224:227], v[76:79]
	v_mfma_f32_16x16x32_bf16 v[128:131], v[136:139], v[196:199], v[128:131]
	v_mfma_f32_16x16x32_bf16 v[124:127], v[144:147], v[196:199], v[124:127]
	v_mfma_f32_16x16x32_bf16 v[112:115], v[136:139], v[204:207], v[112:115]
	v_mfma_f32_16x16x32_bf16 v[108:111], v[144:147], v[204:207], v[108:111]
	v_mfma_f32_16x16x32_bf16 v[96:99], v[136:139], v[218:221], v[96:99]
	v_mfma_f32_16x16x32_bf16 v[92:95], v[144:147], v[218:221], v[92:95]
	v_mfma_f32_16x16x32_bf16 v[80:83], v[136:139], v[228:231], v[80:83]
	v_mfma_f32_16x16x32_bf16 v[76:79], v[144:147], v[228:231], v[76:79]
	s_setprio 0
	s_setprio 1
	v_mfma_f32_16x16x32_bf16 v[120:123], v[148:151], v[174:177], v[120:123]
	v_mfma_f32_16x16x32_bf16 v[116:119], v[156:159], v[174:177], v[116:119]
	v_mfma_f32_16x16x32_bf16 v[104:107], v[148:151], v[200:203], v[104:107]
	v_mfma_f32_16x16x32_bf16 v[100:103], v[156:159], v[200:203], v[100:103]
	v_mfma_f32_16x16x32_bf16 v[88:91], v[148:151], v[208:211], v[88:91]
	v_mfma_f32_16x16x32_bf16 v[84:87], v[156:159], v[208:211], v[84:87]
	v_mfma_f32_16x16x32_bf16 v[72:75], v[148:151], v[224:227], v[72:75]
	v_mfma_f32_16x16x32_bf16 v[68:71], v[156:159], v[224:227], v[68:71]
	v_mfma_f32_16x16x32_bf16 v[120:123], v[152:155], v[196:199], v[120:123]
	v_mfma_f32_16x16x32_bf16 v[116:119], v[170:173], v[196:199], v[116:119]
	v_mfma_f32_16x16x32_bf16 v[104:107], v[152:155], v[204:207], v[104:107]
	v_mfma_f32_16x16x32_bf16 v[100:103], v[170:173], v[204:207], v[100:103]
	v_mfma_f32_16x16x32_bf16 v[88:91], v[152:155], v[218:221], v[88:91]
	v_mfma_f32_16x16x32_bf16 v[84:87], v[170:173], v[218:221], v[84:87]
	v_mfma_f32_16x16x32_bf16 v[72:75], v[152:155], v[228:231], v[72:75]
	v_mfma_f32_16x16x32_bf16 v[68:71], v[170:173], v[228:231], v[68:71]
	s_setprio 0
	s_barrier
	s_add_i32 s40, s44, s53
	s_mov_b32 m0, s40
	ds_read_b128 v[174:177], v194 offset:49152
	ds_read_b128 v[196:199], v194 offset:50176
	ds_read_b128 v[200:203], v194 offset:51200
	ds_read_b128 v[204:207], v194 offset:52224
	ds_read_b128 v[208:211], v194 offset:53248
	ds_read_b128 v[218:221], v194 offset:54272
	ds_read_b128 v[224:227], v194 offset:55296
	ds_read_b128 v[228:231], v194 offset:56320
	s_add_u32 s100, s48, 0x80
	s_addc_u32 s101, s49, 0
	global_load_lds_dwordx4 v162, s[100:101]
	s_add_i32 m0, s40, 0x2000
	s_add_u32 s40, s48, 0xb0080
	s_addc_u32 s41, s49, 0
	s_add_i32 s44, s45, s53
	s_add_u32 s100, s48, 0x80
	s_addc_u32 s101, s49, 0
	global_load_lds_dwordx4 v0, s[100:101]
	s_mov_b32 m0, s44
	s_nop 0
	global_load_lds_dwordx4 v162, s[40:41]
	s_add_i32 m0, s44, 0x2000
	s_nop 0
	global_load_lds_dwordx4 v0, s[40:41]
	s_mov_b32 m0, s64
	s_nop 0
	s_add_u32 s100, s50, 0x80
	s_addc_u32 s101, s51, 0
	global_load_lds_dwordx4 v164, s[100:101]
	s_mov_b32 m0, s65
	s_nop 0
	s_add_u32 s100, s50, 0x80
	s_addc_u32 s101, s51, 0
	global_load_lds_dwordx4 v160, s[100:101]
	s_waitcnt vmcnt(8)
	s_waitcnt lgkmcnt(0)
	s_barrier
	s_setprio 1
	s_waitcnt lgkmcnt(0)
	v_mfma_f32_16x16x32_bf16 v[64:67], v[132:135], v[174:177], v[64:67]
	v_mfma_f32_16x16x32_bf16 v[60:63], v[140:143], v[174:177], v[60:63]
	v_mfma_f32_16x16x32_bf16 v[48:51], v[132:135], v[200:203], v[48:51]
	v_mfma_f32_16x16x32_bf16 v[44:47], v[140:143], v[200:203], v[44:47]
	v_mfma_f32_16x16x32_bf16 v[32:35], v[132:135], v[208:211], v[32:35]
	v_mfma_f32_16x16x32_bf16 v[28:31], v[140:143], v[208:211], v[28:31]
	v_mfma_f32_16x16x32_bf16 v[16:19], v[132:135], v[224:227], v[16:19]
	v_mfma_f32_16x16x32_bf16 v[12:15], v[140:143], v[224:227], v[12:15]
	v_mfma_f32_16x16x32_bf16 v[64:67], v[136:139], v[196:199], v[64:67]
	v_mfma_f32_16x16x32_bf16 v[60:63], v[144:147], v[196:199], v[60:63]
	v_mfma_f32_16x16x32_bf16 v[48:51], v[136:139], v[204:207], v[48:51]
	v_mfma_f32_16x16x32_bf16 v[44:47], v[144:147], v[204:207], v[44:47]
	v_mfma_f32_16x16x32_bf16 v[32:35], v[136:139], v[218:221], v[32:35]
	v_mfma_f32_16x16x32_bf16 v[28:31], v[144:147], v[218:221], v[28:31]
	v_mfma_f32_16x16x32_bf16 v[16:19], v[136:139], v[228:231], v[16:19]
	v_mfma_f32_16x16x32_bf16 v[12:15], v[144:147], v[228:231], v[12:15]
	s_setprio 0
	s_setprio 1
	v_mfma_f32_16x16x32_bf16 v[56:59], v[148:151], v[174:177], v[56:59]
	v_mfma_f32_16x16x32_bf16 v[52:55], v[156:159], v[174:177], v[52:55]
	v_mfma_f32_16x16x32_bf16 v[40:43], v[148:151], v[200:203], v[40:43]
	v_mfma_f32_16x16x32_bf16 v[36:39], v[156:159], v[200:203], v[36:39]
	v_mfma_f32_16x16x32_bf16 v[24:27], v[148:151], v[208:211], v[24:27]
	v_mfma_f32_16x16x32_bf16 v[20:23], v[156:159], v[208:211], v[20:23]
	v_mfma_f32_16x16x32_bf16 v[8:11], v[148:151], v[224:227], v[8:11]
	v_mfma_f32_16x16x32_bf16 v[4:7], v[156:159], v[224:227], v[4:7]
	v_mfma_f32_16x16x32_bf16 v[56:59], v[152:155], v[196:199], v[56:59]
	v_mfma_f32_16x16x32_bf16 v[52:55], v[170:173], v[196:199], v[52:55]
	v_mfma_f32_16x16x32_bf16 v[40:43], v[152:155], v[204:207], v[40:43]
	v_mfma_f32_16x16x32_bf16 v[36:39], v[170:173], v[204:207], v[36:39]
	v_mfma_f32_16x16x32_bf16 v[24:27], v[152:155], v[218:221], v[24:27]
	v_mfma_f32_16x16x32_bf16 v[20:23], v[170:173], v[218:221], v[20:23]
	v_mfma_f32_16x16x32_bf16 v[8:11], v[152:155], v[228:231], v[8:11]
	v_mfma_f32_16x16x32_bf16 v[4:7], v[170:173], v[228:231], v[4:7]
	s_setprio 0
	s_barrier
	s_add_i32 s97, s97, 2
	s_add_u32 s89, s89, 0x100
	s_addc_u32 s90, s90, 0
	s_cmp_gt_u32 s97, 41
	s_mov_b64 s[44:45], s[46:47]
	s_cbranch_scc0 .LBB0_624
	s_and_b64 vcc, exec, s[18:19]
	s_cbranch_vccz .LBB0_627
	s_barrier

.LBB0_668:
	s_add_u32 s36, s26, 0x100
	s_addc_u32 s37, s27, 0
	s_add_i32 s40, 0, 0x10000
	s_cmp_eq_u32 s69, 40
	s_cselect_b32 s47, s11, s37
	s_cselect_b32 s46, s10, s36
	s_cselect_b32 s45, s19, s68
	s_cselect_b32 s44, s18, s65
	s_add_i32 s41, 0, 0x14000
	v_add_u32_e32 v144, s40, v187
	v_add_u32_e32 v160, s41, v187
	ds_read_b128 v[132:135], v144
	ds_read_b128 v[136:139], v144 offset:1024
	ds_read_b128 v[140:143], v144 offset:2048
	ds_read_b128 v[144:147], v144 offset:3072
	ds_read_b128 v[148:151], v160
	ds_read_b128 v[152:155], v160 offset:1024
	ds_read_b128 v[156:159], v160 offset:2048
	ds_read_b128 v[160:163], v160 offset:3072
	s_add_i32 m0, s49, 0xc000
	ds_read_b128 v[164:167], v229
	ds_read_b128 v[168:171], v229 offset:1024
	ds_read_b128 v[172:175], v229 offset:2048
	ds_read_b128 v[176:179], v229 offset:3072
	ds_read_b128 v[200:203], v229 offset:4096
	ds_read_b128 v[204:207], v229 offset:5120
	ds_read_b128 v[208:211], v229 offset:6144
	ds_read_b128 v[218:221], v229 offset:7168
	global_load_lds_dwordx4 v196, s[26:27]
	s_add_i32 m0, s49, 0xe000
	s_nop 0
	global_load_lds_dwordx4 v198, s[26:27]
	s_waitcnt vmcnt(8)
	s_waitcnt lgkmcnt(0)
	s_barrier
	s_setprio 1
	s_waitcnt lgkmcnt(0)
	v_mfma_f32_16x16x32_bf16 v[128:131], v[132:135], v[164:167], v[128:131]
	v_mfma_f32_16x16x32_bf16 v[124:127], v[140:143], v[164:167], v[124:127]
	v_mfma_f32_16x16x32_bf16 v[112:115], v[132:135], v[172:175], v[112:115]
	v_mfma_f32_16x16x32_bf16 v[108:111], v[140:143], v[172:175], v[108:111]
	v_mfma_f32_16x16x32_bf16 v[96:99], v[132:135], v[200:203], v[96:99]
	v_mfma_f32_16x16x32_bf16 v[92:95], v[140:143], v[200:203], v[92:95]
	v_mfma_f32_16x16x32_bf16 v[80:83], v[132:135], v[208:211], v[80:83]
	v_mfma_f32_16x16x32_bf16 v[76:79], v[140:143], v[208:211], v[76:79]
	v_mfma_f32_16x16x32_bf16 v[128:131], v[136:139], v[168:171], v[128:131]
	v_mfma_f32_16x16x32_bf16 v[124:127], v[144:147], v[168:171], v[124:127]
	v_mfma_f32_16x16x32_bf16 v[112:115], v[136:139], v[176:179], v[112:115]
	v_mfma_f32_16x16x32_bf16 v[108:111], v[144:147], v[176:179], v[108:111]
	v_mfma_f32_16x16x32_bf16 v[96:99], v[136:139], v[204:207], v[96:99]
	v_mfma_f32_16x16x32_bf16 v[92:95], v[144:147], v[204:207], v[92:95]
	v_mfma_f32_16x16x32_bf16 v[80:83], v[136:139], v[218:221], v[80:83]
	v_mfma_f32_16x16x32_bf16 v[76:79], v[144:147], v[218:221], v[76:79]
	s_setprio 0
	s_setprio 1
	v_mfma_f32_16x16x32_bf16 v[120:123], v[148:151], v[164:167], v[120:123]
	v_mfma_f32_16x16x32_bf16 v[116:119], v[156:159], v[164:167], v[116:119]
	v_mfma_f32_16x16x32_bf16 v[104:107], v[148:151], v[172:175], v[104:107]
	v_mfma_f32_16x16x32_bf16 v[100:103], v[156:159], v[172:175], v[100:103]
	v_mfma_f32_16x16x32_bf16 v[88:91], v[148:151], v[200:203], v[88:91]
	v_mfma_f32_16x16x32_bf16 v[84:87], v[156:159], v[200:203], v[84:87]
	v_mfma_f32_16x16x32_bf16 v[72:75], v[148:151], v[208:211], v[72:75]
	v_mfma_f32_16x16x32_bf16 v[68:71], v[156:159], v[208:211], v[68:71]
	v_mfma_f32_16x16x32_bf16 v[120:123], v[152:155], v[168:171], v[120:123]
	v_mfma_f32_16x16x32_bf16 v[116:119], v[160:163], v[168:171], v[116:119]
	v_mfma_f32_16x16x32_bf16 v[104:107], v[152:155], v[176:179], v[104:107]
	v_mfma_f32_16x16x32_bf16 v[100:103], v[160:163], v[176:179], v[100:103]
	v_mfma_f32_16x16x32_bf16 v[88:91], v[152:155], v[204:207], v[88:91]
	v_mfma_f32_16x16x32_bf16 v[84:87], v[160:163], v[204:207], v[84:87]
	v_mfma_f32_16x16x32_bf16 v[72:75], v[152:155], v[218:221], v[72:75]
	v_mfma_f32_16x16x32_bf16 v[68:71], v[160:163], v[218:221], v[68:71]
	s_setprio 0
	s_barrier
	s_add_i32 s26, s40, s48
	s_mov_b32 m0, s26
	ds_read_b128 v[164:167], v229 offset:16384
	ds_read_b128 v[168:171], v229 offset:17408
	ds_read_b128 v[172:175], v229 offset:18432
	ds_read_b128 v[176:179], v229 offset:19456
	ds_read_b128 v[200:203], v229 offset:20480
	ds_read_b128 v[204:207], v229 offset:21504
	ds_read_b128 v[208:211], v229 offset:22528
	ds_read_b128 v[218:221], v229 offset:23552
	global_load_lds_dwordx4 v192, s[44:45]
	s_add_i32 m0, s26, 0x2000
	s_add_u32 s26, s44, 0xb0000
	s_addc_u32 s27, s45, 0
	s_add_i32 s40, s41, s48
	global_load_lds_dwordx4 v0, s[44:45]
	s_mov_b32 m0, s40
	s_nop 0
	global_load_lds_dwordx4 v192, s[26:27]
	s_add_i32 m0, s40, 0x2000
	s_nop 0
	global_load_lds_dwordx4 v0, s[26:27]
	s_mov_b32 m0, s49
	s_nop 0
	global_load_lds_dwordx4 v194, s[46:47]
	s_mov_b32 m0, s50
	s_nop 0
	global_load_lds_dwordx4 v190, s[46:47]
	s_waitcnt vmcnt(8)
	s_waitcnt lgkmcnt(0)
	s_barrier
	s_setprio 1
	s_waitcnt lgkmcnt(0)
	v_mfma_f32_16x16x32_bf16 v[64:67], v[132:135], v[164:167], v[64:67]
	v_mfma_f32_16x16x32_bf16 v[60:63], v[140:143], v[164:167], v[60:63]
	v_mfma_f32_16x16x32_bf16 v[48:51], v[132:135], v[172:175], v[48:51]
	v_mfma_f32_16x16x32_bf16 v[44:47], v[140:143], v[172:175], v[44:47]
	v_mfma_f32_16x16x32_bf16 v[32:35], v[132:135], v[200:203], v[32:35]
	v_mfma_f32_16x16x32_bf16 v[28:31], v[140:143], v[200:203], v[28:31]
	v_mfma_f32_16x16x32_bf16 v[16:19], v[132:135], v[208:211], v[16:19]
	v_mfma_f32_16x16x32_bf16 v[12:15], v[140:143], v[208:211], v[12:15]
	v_mfma_f32_16x16x32_bf16 v[64:67], v[136:139], v[168:171], v[64:67]
	v_mfma_f32_16x16x32_bf16 v[60:63], v[144:147], v[168:171], v[60:63]
	v_mfma_f32_16x16x32_bf16 v[48:51], v[136:139], v[176:179], v[48:51]
	v_mfma_f32_16x16x32_bf16 v[44:47], v[144:147], v[176:179], v[44:47]
	v_mfma_f32_16x16x32_bf16 v[32:35], v[136:139], v[204:207], v[32:35]
	v_mfma_f32_16x16x32_bf16 v[28:31], v[144:147], v[204:207], v[28:31]
	v_mfma_f32_16x16x32_bf16 v[16:19], v[136:139], v[218:221], v[16:19]
	v_mfma_f32_16x16x32_bf16 v[12:15], v[144:147], v[218:221], v[12:15]
	s_setprio 0
	s_setprio 1
	v_mfma_f32_16x16x32_bf16 v[56:59], v[148:151], v[164:167], v[56:59]
	v_mfma_f32_16x16x32_bf16 v[52:55], v[156:159], v[164:167], v[52:55]
	v_mfma_f32_16x16x32_bf16 v[40:43], v[148:151], v[172:175], v[40:43]
	v_mfma_f32_16x16x32_bf16 v[36:39], v[156:159], v[172:175], v[36:39]
	v_mfma_f32_16x16x32_bf16 v[24:27], v[148:151], v[200:203], v[24:27]
	v_mfma_f32_16x16x32_bf16 v[20:23], v[156:159], v[200:203], v[20:23]
	v_mfma_f32_16x16x32_bf16 v[8:11], v[148:151], v[208:211], v[8:11]
	v_mfma_f32_16x16x32_bf16 v[4:7], v[156:159], v[208:211], v[4:7]
	v_mfma_f32_16x16x32_bf16 v[56:59], v[152:155], v[168:171], v[56:59]
	v_mfma_f32_16x16x32_bf16 v[52:55], v[160:163], v[168:171], v[52:55]
	v_mfma_f32_16x16x32_bf16 v[40:43], v[152:155], v[176:179], v[40:43]
	v_mfma_f32_16x16x32_bf16 v[36:39], v[160:163], v[176:179], v[36:39]
	v_mfma_f32_16x16x32_bf16 v[24:27], v[152:155], v[204:207], v[24:27]
	v_mfma_f32_16x16x32_bf16 v[20:23], v[160:163], v[204:207], v[20:23]
	v_mfma_f32_16x16x32_bf16 v[8:11], v[152:155], v[218:221], v[8:11]
	v_mfma_f32_16x16x32_bf16 v[4:7], v[160:163], v[218:221], v[4:7]
	s_setprio 0
	s_barrier
	s_add_i32 s40, 0, 0x18000
	s_add_i32 s41, 0, 0x1c000
	v_add_u32_e32 v144, s40, v187
	v_add_u32_e32 v160, s41, v187
	ds_read_b128 v[132:135], v144
	ds_read_b128 v[136:139], v144 offset:1024
	ds_read_b128 v[140:143], v144 offset:2048
	ds_read_b128 v[144:147], v144 offset:3072
	ds_read_b128 v[148:151], v160
	ds_read_b128 v[152:155], v160 offset:1024
	ds_read_b128 v[156:159], v160 offset:2048
	ds_read_b128 v[160:163], v160 offset:3072
	s_add_u32 s26, s46, 0xb0000
	s_addc_u32 s27, s47, 0
	s_mov_b32 m0, s51
	ds_read_b128 v[164:167], v229 offset:32768
	ds_read_b128 v[168:171], v229 offset:33792
	ds_read_b128 v[172:175], v229 offset:34816
	ds_read_b128 v[176:179], v229 offset:35840
	ds_read_b128 v[200:203], v229 offset:36864
	ds_read_b128 v[204:207], v229 offset:37888
	ds_read_b128 v[208:211], v229 offset:38912
	ds_read_b128 v[218:221], v229 offset:39936
	global_load_lds_dwordx4 v194, s[26:27]
	s_mov_b32 m0, s53
	s_nop 0
	global_load_lds_dwordx4 v190, s[26:27]
	s_waitcnt vmcnt(8)
	s_waitcnt lgkmcnt(0)
	s_barrier
	s_setprio 1
	s_waitcnt lgkmcnt(0)
	v_mfma_f32_16x16x32_bf16 v[128:131], v[132:135], v[164:167], v[128:131]
	v_mfma_f32_16x16x32_bf16 v[124:127], v[140:143], v[164:167], v[124:127]
	v_mfma_f32_16x16x32_bf16 v[112:115], v[132:135], v[172:175], v[112:115]
	v_mfma_f32_16x16x32_bf16 v[108:111], v[140:143], v[172:175], v[108:111]
	v_mfma_f32_16x16x32_bf16 v[96:99], v[132:135], v[200:203], v[96:99]
	v_mfma_f32_16x16x32_bf16 v[92:95], v[140:143], v[200:203], v[92:95]
	v_mfma_f32_16x16x32_bf16 v[80:83], v[132:135], v[208:211], v[80:83]
	v_mfma_f32_16x16x32_bf16 v[76:79], v[140:143], v[208:211], v[76:79]
	v_mfma_f32_16x16x32_bf16 v[128:131], v[136:139], v[168:171], v[128:131]
	v_mfma_f32_16x16x32_bf16 v[124:127], v[144:147], v[168:171], v[124:127]
	v_mfma_f32_16x16x32_bf16 v[112:115], v[136:139], v[176:179], v[112:115]
	v_mfma_f32_16x16x32_bf16 v[108:111], v[144:147], v[176:179], v[108:111]
	v_mfma_f32_16x16x32_bf16 v[96:99], v[136:139], v[204:207], v[96:99]
	v_mfma_f32_16x16x32_bf16 v[92:95], v[144:147], v[204:207], v[92:95]
	v_mfma_f32_16x16x32_bf16 v[80:83], v[136:139], v[218:221], v[80:83]
	v_mfma_f32_16x16x32_bf16 v[76:79], v[144:147], v[218:221], v[76:79]
	s_setprio 0
	s_setprio 1
	v_mfma_f32_16x16x32_bf16 v[120:123], v[148:151], v[164:167], v[120:123]
	v_mfma_f32_16x16x32_bf16 v[116:119], v[156:159], v[164:167], v[116:119]
	v_mfma_f32_16x16x32_bf16 v[104:107], v[148:151], v[172:175], v[104:107]
	v_mfma_f32_16x16x32_bf16 v[100:103], v[156:159], v[172:175], v[100:103]
	v_mfma_f32_16x16x32_bf16 v[88:91], v[148:151], v[200:203], v[88:91]
	v_mfma_f32_16x16x32_bf16 v[84:87], v[156:159], v[200:203], v[84:87]
	v_mfma_f32_16x16x32_bf16 v[72:75], v[148:151], v[208:211], v[72:75]
	v_mfma_f32_16x16x32_bf16 v[68:71], v[156:159], v[208:211], v[68:71]
	v_mfma_f32_16x16x32_bf16 v[120:123], v[152:155], v[168:171], v[120:123]
	v_mfma_f32_16x16x32_bf16 v[116:119], v[160:163], v[168:171], v[116:119]
	v_mfma_f32_16x16x32_bf16 v[104:107], v[152:155], v[176:179], v[104:107]
	v_mfma_f32_16x16x32_bf16 v[100:103], v[160:163], v[176:179], v[100:103]
	v_mfma_f32_16x16x32_bf16 v[88:91], v[152:155], v[204:207], v[88:91]
	v_mfma_f32_16x16x32_bf16 v[84:87], v[160:163], v[204:207], v[84:87]
	v_mfma_f32_16x16x32_bf16 v[72:75], v[152:155], v[218:221], v[72:75]
	v_mfma_f32_16x16x32_bf16 v[68:71], v[160:163], v[218:221], v[68:71]
	s_setprio 0
	s_barrier
	s_add_i32 s26, s40, s48
	s_mov_b32 m0, s26
	ds_read_b128 v[164:167], v229 offset:49152
	ds_read_b128 v[168:171], v229 offset:50176
	ds_read_b128 v[172:175], v229 offset:51200
	ds_read_b128 v[176:179], v229 offset:52224
	ds_read_b128 v[200:203], v229 offset:53248
	ds_read_b128 v[204:207], v229 offset:54272
	ds_read_b128 v[208:211], v229 offset:55296
	ds_read_b128 v[218:221], v229 offset:56320
	s_add_u32 s100, s44, 0x80
	s_addc_u32 s101, s45, 0
	global_load_lds_dwordx4 v192, s[100:101]
	s_add_i32 m0, s26, 0x2000
	s_add_u32 s26, s44, 0xb0080
	s_addc_u32 s27, s45, 0
	s_add_i32 s40, s41, s48
	s_add_u32 s100, s44, 0x80
	s_addc_u32 s101, s45, 0
	global_load_lds_dwordx4 v0, s[100:101]
	s_mov_b32 m0, s40
	s_nop 0
	global_load_lds_dwordx4 v192, s[26:27]
	s_add_i32 m0, s40, 0x2000
	s_nop 0
	global_load_lds_dwordx4 v0, s[26:27]
	s_mov_b32 m0, s54
	s_nop 0
	s_add_u32 s100, s46, 0x80
	s_addc_u32 s101, s47, 0
	global_load_lds_dwordx4 v194, s[100:101]
	s_mov_b32 m0, s55
	s_nop 0
	s_add_u32 s100, s46, 0x80
	s_addc_u32 s101, s47, 0
	global_load_lds_dwordx4 v190, s[100:101]
	s_waitcnt vmcnt(8)
	s_waitcnt lgkmcnt(0)
	s_barrier
	s_setprio 1
	s_waitcnt lgkmcnt(0)
	v_mfma_f32_16x16x32_bf16 v[64:67], v[132:135], v[164:167], v[64:67]
	v_mfma_f32_16x16x32_bf16 v[60:63], v[140:143], v[164:167], v[60:63]
	v_mfma_f32_16x16x32_bf16 v[48:51], v[132:135], v[172:175], v[48:51]
	v_mfma_f32_16x16x32_bf16 v[44:47], v[140:143], v[172:175], v[44:47]
	v_mfma_f32_16x16x32_bf16 v[32:35], v[132:135], v[200:203], v[32:35]
	v_mfma_f32_16x16x32_bf16 v[28:31], v[140:143], v[200:203], v[28:31]
	v_mfma_f32_16x16x32_bf16 v[16:19], v[132:135], v[208:211], v[16:19]
	v_mfma_f32_16x16x32_bf16 v[12:15], v[140:143], v[208:211], v[12:15]
	v_mfma_f32_16x16x32_bf16 v[64:67], v[136:139], v[168:171], v[64:67]
	v_mfma_f32_16x16x32_bf16 v[60:63], v[144:147], v[168:171], v[60:63]
	v_mfma_f32_16x16x32_bf16 v[48:51], v[136:139], v[176:179], v[48:51]
	v_mfma_f32_16x16x32_bf16 v[44:47], v[144:147], v[176:179], v[44:47]
	v_mfma_f32_16x16x32_bf16 v[32:35], v[136:139], v[204:207], v[32:35]
	v_mfma_f32_16x16x32_bf16 v[28:31], v[144:147], v[204:207], v[28:31]
	v_mfma_f32_16x16x32_bf16 v[16:19], v[136:139], v[218:221], v[16:19]
	v_mfma_f32_16x16x32_bf16 v[12:15], v[144:147], v[218:221], v[12:15]
	s_setprio 0
	s_setprio 1
	v_mfma_f32_16x16x32_bf16 v[56:59], v[148:151], v[164:167], v[56:59]
	v_mfma_f32_16x16x32_bf16 v[52:55], v[156:159], v[164:167], v[52:55]
	v_mfma_f32_16x16x32_bf16 v[40:43], v[148:151], v[172:175], v[40:43]
	v_mfma_f32_16x16x32_bf16 v[36:39], v[156:159], v[172:175], v[36:39]
	v_mfma_f32_16x16x32_bf16 v[24:27], v[148:151], v[200:203], v[24:27]
	v_mfma_f32_16x16x32_bf16 v[20:23], v[156:159], v[200:203], v[20:23]
	v_mfma_f32_16x16x32_bf16 v[8:11], v[148:151], v[208:211], v[8:11]
	v_mfma_f32_16x16x32_bf16 v[4:7], v[156:159], v[208:211], v[4:7]
	v_mfma_f32_16x16x32_bf16 v[56:59], v[152:155], v[168:171], v[56:59]
	v_mfma_f32_16x16x32_bf16 v[52:55], v[160:163], v[168:171], v[52:55]
	v_mfma_f32_16x16x32_bf16 v[40:43], v[152:155], v[176:179], v[40:43]
	v_mfma_f32_16x16x32_bf16 v[36:39], v[160:163], v[176:179], v[36:39]
	v_mfma_f32_16x16x32_bf16 v[24:27], v[152:155], v[204:207], v[24:27]
	v_mfma_f32_16x16x32_bf16 v[20:23], v[160:163], v[204:207], v[20:23]
	v_mfma_f32_16x16x32_bf16 v[8:11], v[152:155], v[218:221], v[8:11]
	v_mfma_f32_16x16x32_bf16 v[4:7], v[160:163], v[218:221], v[4:7]
	s_setprio 0
	s_barrier
	s_add_i32 s69, s69, 2
	s_add_u32 s65, s65, 0x100
	s_addc_u32 s68, s68, 0
	s_cmp_gt_u32 s69, 41
	s_mov_b64 s[26:27], s[36:37]
	s_cbranch_scc0 .LBB0_668
	s_and_b64 vcc, exec, s[14:15]
	s_cbranch_vccz .LBB0_671
	s_barrier
